# early L1 invalidate in barrier followers; nt stores for final y and K/V outputs
# speedup vs baseline: 1.0013x; 1.0013x over previous
; __device__ __forceinline__ unsigned xb_ld(unsigned* p)              { return __hip_atomic_load(p, __ATOMIC_RELAXED, __HIP_MEMORY_SCOPE_AGENT); }
; __device__ __forceinline__ unsigned xb_add(unsigned* p, unsigned v) { return __hip_atomic_fetch_add(p, v, __ATOMIC_RELAXED, __HIP_MEMORY_SCOPE_AGENT); }
; #define XB_SPIN(cond, bar) do { unsigned _sp = 0; while (cond) { __builtin_amdgcn_s_sleep(1); \
;     if ((++_sp & 255u) == 0u) { if (xb_ld(&(bar)[XB_TMO])) break; if (_sp > XB_SPIN_CAP) { atomicAdd(&(bar)[XB_TMO], 1u); break; } } } } while (0)
; __device__ __forceinline__ void xcd_barrier(const XcdBarrier& b) {
;     ...
;         const unsigned old = xb_add(&bar[XB_XSUB(b.x)], 1u);
;         const unsigned gen = old / nloc;
;         if (old + 1u == (gen + 1u) * nloc) {
;             __builtin_amdgcn_fence(__ATOMIC_RELEASE, "agent");
;             asm volatile("s_waitcnt vmcnt(0)" ::: "memory");
;             const unsigned og = xb_add(&bar[XB_TOP], 1u);
;             const unsigned tg = og / nx;
;             if (og + 1u == (tg + 1u) * nx) xb_add(&bar[XB_TOPGEN], 1u);
;             else XB_SPIN(xb_ld(&bar[XB_TOPGEN]) == tg, bar);
;             __builtin_amdgcn_fence(__ATOMIC_ACQUIRE, "agent");
;             xb_add(&bar[XB_XGEN(b.x)], 1u);
;             asm volatile("s_waitcnt vmcnt(0)" ::: "memory");
;         } else {
;             XB_SPIN(xb_ld(&bar[XB_XGEN(b.x)]) == gen, bar);
.LBB0_101:
	s_lshl_b32 s2, s97, 8
	s_add_u32 s8, s94, s2
	s_addc_u32 s9, s95, 0
	v_mov_b32_e32 v2, 0x1000
	v_mov_b32_e32 v4, 1
	global_atomic_add v4, v2, v4, s[8:9] offset:1024 sc0
	v_cvt_f32_u32_e32 v2, v3
	v_sub_u32_e32 v5, 0, v3
	v_rcp_iflag_f32_e32 v2, v2
	s_nop 0
	v_mul_f32_e32 v2, 0x4f7ffffe, v2
	v_cvt_u32_f32_e32 v2, v2
	v_mul_lo_u32 v5, v5, v2
	v_mul_hi_u32 v5, v2, v5
	v_add_u32_e32 v2, v2, v5
	s_waitcnt vmcnt(0)
	v_mul_hi_u32 v2, v4, v2
	v_mul_lo_u32 v5, v2, v3
	v_sub_u32_e32 v5, v4, v5
	v_add_u32_e32 v6, 1, v2
	v_cmp_ge_u32_e32 vcc, v5, v3
	v_add_u32_e32 v4, 1, v4
	s_nop 0
	v_cndmask_b32_e32 v2, v2, v6, vcc
	v_sub_u32_e32 v6, v5, v3
	v_cndmask_b32_e32 v5, v5, v6, vcc
	v_add_u32_e32 v6, 1, v2
	v_cmp_ge_u32_e32 vcc, v5, v3
	s_nop 1
	v_cndmask_b32_e32 v2, v2, v6, vcc
	v_mul_lo_u32 v5, v3, v2
	v_add_u32_e32 v3, v5, v3
	v_cmp_ne_u32_e32 vcc, v4, v3
	s_and_saveexec_b64 s[2:3], vcc
	s_xor_b64 s[10:11], exec, s[2:3]
	s_cbranch_execz .LBB0_115
	s_waitcnt lgkmcnt(0)
	buffer_inv sc1
	v_mov_b32_e32 v1, 0x2000
	global_load_dword v1, v1, s[8:9] offset:1024 sc1
	s_add_u32 s16, s8, 0x2400
	s_addc_u32 s17, s9, 0
	s_waitcnt vmcnt(0)
	v_cmp_eq_u32_e32 vcc, v1, v2
	s_and_saveexec_b64 s[12:13], vcc
	s_cbranch_execz .LBB0_114
	s_load_dwordx8 s[20:27], s[0:1], 0x100
	s_mov_b32 s2, 1
	s_mov_b64 s[18:19], 0
	v_mov_b32_e32 v1, 0
	s_waitcnt lgkmcnt(0)
	s_add_u32 s14, s26, 0x4200
	s_addc_u32 s15, s27, 0
	s_branch .LBB0_105

; __device__ __forceinline__ unsigned xb_ld(unsigned* p)              { return __hip_atomic_load(p, __ATOMIC_RELAXED, __HIP_MEMORY_SCOPE_AGENT); }
; #define XB_SPIN(cond, bar) do { unsigned _sp = 0; while (cond) { __builtin_amdgcn_s_sleep(1); \
;     if ((++_sp & 255u) == 0u) { if (xb_ld(&(bar)[XB_TMO])) break; if (_sp > XB_SPIN_CAP) { atomicAdd(&(bar)[XB_TMO], 1u); break; } } } } while (0)
; __device__ __forceinline__ void xcd_barrier(const XcdBarrier& b) {
;     ...
;             XB_SPIN(xb_ld(&bar[XB_XGEN(b.x)]) == gen, bar);
;             __builtin_amdgcn_fence(__ATOMIC_ACQUIRE, "agent");
;             asm volatile("s_waitcnt vmcnt(0)" ::: "memory");
.LBB0_114:
	s_or_b64 exec, exec, s[12:13]
	s_waitcnt vmcnt(0)
	s_waitcnt vmcnt(0)

; DI void qkv_row(const Params& p, const bf16* PROJ, int m, int lane, float* kout, float* vout, u32x4& vraw) {
;     bf16* QB = (bf16*)(p.ws + WS_QB); bf16* KB = (bf16*)(p.ws + WS_KB);
;     const bf16* pr = PROJ + (size_t)m * EVEN_IN;
;     const u32x4 q8 = *(const u32x4*)(pr + 8 * lane), k8 = *(const u32x4*)(pr + SBW + 8 * lane), v8 = *(const u32x4*)(pr + 2 * SBW + 8 * lane);
;     float q[8], k[8], v[8];
; #pragma unroll
;     for (int j = 0; j < 4; ++j) { q[2 * j] = bflo(q8[j]); q[2 * j + 1] = bfhi(q8[j]); k[2 * j] = bflo(k8[j]); k[2 * j + 1] = bfhi(k8[j]); v[2 * j] = bflo(v8[j]); v[2 * j + 1] = bfhi(v8[j]); }
;     float sq = 0.f, sk = 0.f;
; #pragma unroll
;     for (int j = 0; j < 8; ++j) { sq += q[j] * q[j]; sk += k[j] * k[j]; }
; #pragma unroll
;     for (int o = 1; o < 8; o <<= 1) { sq += __shfl_xor(sq, o); sk += __shfl_xor(sk, o); }
;     const float rq = frsq(sq * (1.f / SBD) + EPS) * (0.125f * LOG2E), rk = frsq(sk * (1.f / SBD) + EPS);
;     const float* qg = (const float*)p.in[I_QG] + 8 * (lane & 7); const float* kg = (const float*)p.in[I_KG] + 8 * (lane & 7);
;     const f32x4 qg0 = *(const f32x4*)qg, qg1 = *(const f32x4*)(qg + 4), kg0 = *(const f32x4*)kg, kg1 = *(const f32x4*)(kg + 4);
;     float qn[8], kn[8];
; #pragma unroll
;     for (int j = 0; j < 4; ++j) { qn[j] = q[j] * rq * qg0[j]; qn[4 + j] = q[4 + j] * rq * qg1[j]; kn[j] = k[j] * rk * kg0[j]; kn[4 + j] = k[4 + j] * rk * kg1[j]; }
;     u32x4 qo, ko;
; #pragma unroll
;     for (int j = 0; j < 4; ++j) { qo[j] = pk2(qn[2 * j], qn[2 * j + 1]); ko[j] = pk2(kn[2 * j], kn[2 * j + 1]); }
;     *(u32x4*)(QB + (size_t)m * SBW + 8 * lane) = qo; *(u32x4*)(KB + (size_t)m * SBW + 8 * lane) = ko;
;     *(f32x4*)(kout + 8 * lane) = (f32x4){kn[0], kn[1], kn[2], kn[3]}; *(f32x4*)(kout + 8 * lane + 4) = (f32x4){kn[4], kn[5], kn[6], kn[7]};
;     *(f32x4*)(vout + 8 * lane) = (f32x4){v[0], v[1], v[2], v[3]}; *(f32x4*)(vout + 8 * lane + 4) = (f32x4){v[4], v[5], v[6], v[7]};
;     vraw = v8;
; }
; DI void phase_even_a(const Params& p, LAS unsigned char* lds, int tid, int lane_, int wave, int G) {
;     ...
;             for (int i = 0; i < 8; ++i) { const int tl = wave * 8 + i, m = m0 + tl; u32x4 vraw;
;                 qkv_row(p, PROJ, m, lane, p.out + O_KP + (size_t)m * SBW, p.out + O_VP + (size_t)m * SBW, vraw);
;                 *(LAS u32x4*)(vt + tl * VLD + 8 * lane) = vraw; }
.LBB0_454:
	v_lshl_add_u64 v[36:37], s[14:15], 0, v[66:67]
	v_add_co_u32_e32 v2, vcc, 0xe900000, v36
	s_mov_b32 s4, 0x17600000
	s_nop 0
	v_addc_co_u32_e32 v3, vcc, 0, v37, vcc
	global_load_dwordx4 v[14:17], v[2:3], off
	global_load_dwordx4 v[18:21], v[2:3], off offset:1024
	s_nop 0
	global_load_dwordx4 v[2:5], v[2:3], off offset:2048
	s_nop 0
	global_load_dwordx4 v[22:25], v[30:31], off offset:16
	global_load_dwordx4 v[26:29], v[30:31], off
	global_load_dwordx4 v[42:45], v[32:33], off offset:16
	global_load_dwordx4 v[46:49], v[32:33], off
	s_add_u32 s14, s14, 0x2800
	s_addc_u32 s15, s15, 0
	s_waitcnt vmcnt(6)
	v_lshlrev_b32_e32 v60, 16, v14
	v_and_b32_e32 v61, 0xffff0000, v14
	v_lshlrev_b32_e32 v56, 16, v15
	v_and_b32_e32 v57, 0xffff0000, v15
	v_pk_mul_f32 v[14:15], v[60:61], v[60:61]
	v_pk_mul_f32 v[58:59], v[56:57], v[56:57]
	v_add_f32_e32 v14, v14, v15
	v_lshlrev_b32_e32 v54, 16, v16
	v_and_b32_e32 v55, 0xffff0000, v16
	v_add_f32_e32 v14, v58, v14
	v_lshlrev_b32_e32 v50, 16, v17
	v_and_b32_e32 v51, 0xffff0000, v17
	v_pk_mul_f32 v[16:17], v[54:55], v[54:55]
	v_add_f32_e32 v14, v59, v14
	v_add_f32_e32 v14, v16, v14
	v_pk_mul_f32 v[52:53], v[50:51], v[50:51]
	v_add_f32_e32 v14, v17, v14
	v_add_f32_e32 v14, v52, v14
	v_add_f32_e32 v14, v53, v14
	ds_bpermute_b32 v15, v38, v14
	s_waitcnt vmcnt(4)
	v_lshlrev_b32_e32 v6, 16, v2
	v_and_b32_e32 v7, 0xffff0000, v2
	v_lshlrev_b32_e32 v8, 16, v3
	v_and_b32_e32 v9, 0xffff0000, v3
	s_waitcnt lgkmcnt(0)
	v_add_f32_e32 v14, v14, v15
	ds_bpermute_b32 v15, v39, v14
	v_lshlrev_b32_e32 v10, 16, v4
	v_and_b32_e32 v11, 0xffff0000, v4
	v_lshlrev_b32_e32 v12, 16, v5
	v_and_b32_e32 v13, 0xffff0000, v5
	s_waitcnt lgkmcnt(0)
	v_add_f32_e32 v14, v14, v15
	ds_bpermute_b32 v15, v40, v14
	s_waitcnt lgkmcnt(0)
	v_add_f32_e32 v14, v14, v15
	v_fmamk_f32 v14, v14, 0x3c800000, v214
	v_rsq_f32_e32 v14, v14
	s_nop 0
	v_mul_f32_e32 v14, 0x3e38aa3b, v14
	v_pk_mul_f32 v[16:17], v[14:15], v[60:61] op_sel_hi:[0,1]
	s_waitcnt vmcnt(2)
	v_pk_mul_f32 v[26:27], v[26:27], v[16:17]
	v_pk_mul_f32 v[16:17], v[14:15], v[54:55] op_sel_hi:[0,1]
	v_pk_mul_f32 v[52:53], v[22:23], v[16:17]
	v_pk_mul_f32 v[16:17], v[14:15], v[56:57] op_sel_hi:[0,1]
	v_pk_mul_f32 v[14:15], v[14:15], v[50:51] op_sel_hi:[0,1]
	v_lshlrev_b32_e32 v56, 16, v18
	v_and_b32_e32 v57, 0xffff0000, v18
	v_pk_mul_f32 v[50:51], v[24:25], v[14:15]
	v_lshlrev_b32_e32 v24, 16, v19
	v_and_b32_e32 v25, 0xffff0000, v19
	v_pk_mul_f32 v[18:19], v[56:57], v[56:57]
	v_pk_mul_f32 v[54:55], v[24:25], v[24:25]
	v_add_f32_e32 v18, v18, v19
	v_pk_mul_f32 v[28:29], v[28:29], v[16:17]
	v_lshlrev_b32_e32 v16, 16, v20
	v_and_b32_e32 v17, 0xffff0000, v20
	v_add_f32_e32 v18, v54, v18
	v_lshlrev_b32_e32 v22, 16, v21
	v_and_b32_e32 v23, 0xffff0000, v21
	v_pk_mul_f32 v[20:21], v[16:17], v[16:17]
	v_add_f32_e32 v18, v55, v18
	v_add_f32_e32 v18, v20, v18
	v_pk_mul_f32 v[14:15], v[22:23], v[22:23]
	v_add_f32_e32 v18, v21, v18
	v_add_f32_e32 v14, v14, v18
	v_add_f32_e32 v14, v15, v14
	ds_bpermute_b32 v15, v38, v14
	v_cvt_pk_bf16_f32 v26, v26, v27
	v_cvt_pk_bf16_f32 v27, v28, v29
	v_cvt_pk_bf16_f32 v29, v50, v51
	v_cvt_pk_bf16_f32 v28, v52, v53
	s_waitcnt lgkmcnt(0)
	v_add_f32_e32 v14, v14, v15
	ds_bpermute_b32 v15, v39, v14
	s_waitcnt lgkmcnt(0)
	v_add_f32_e32 v14, v14, v15
	ds_bpermute_b32 v15, v40, v14
	s_waitcnt lgkmcnt(0)
	v_add_f32_e32 v14, v14, v15
	v_fmamk_f32 v14, v14, 0x3c800000, v214
	v_rsq_f32_e32 v20, v14
	s_nop 0
	v_pk_mul_f32 v[16:17], v[20:21], v[16:17] op_sel_hi:[0,1]
	s_waitcnt vmcnt(1)
	v_pk_mul_f32 v[18:19], v[42:43], v[16:17]
	v_lshl_add_u64 v[42:43], s[16:17], 0, v[66:67]
	v_add_co_u32_e32 v50, vcc, s4, v42
	v_pk_mul_f32 v[14:15], v[20:21], v[56:57] op_sel_hi:[0,1]
	v_pk_mul_f32 v[16:17], v[20:21], v[24:25] op_sel_hi:[0,1]
	v_pk_mul_f32 v[20:21], v[20:21], v[22:23] op_sel_hi:[0,1]
	v_addc_co_u32_e32 v51, vcc, 0, v43, vcc
	s_mov_b32 s4, 0x18700000
	s_waitcnt vmcnt(0)
	v_pk_mul_f32 v[14:15], v[46:47], v[14:15]
	v_pk_mul_f32 v[16:17], v[48:49], v[16:17]
	v_pk_mul_f32 v[20:21], v[44:45], v[20:21]
	v_add_co_u32_e32 v52, vcc, s4, v42
	v_cvt_pk_bf16_f32 v22, v14, v15
	v_cvt_pk_bf16_f32 v23, v16, v17
	v_cvt_pk_bf16_f32 v24, v18, v19
	v_cvt_pk_bf16_f32 v25, v20, v21
	v_addc_co_u32_e32 v53, vcc, 0, v43, vcc
	global_store_dwordx4 v[52:53], v[22:25], off
	s_mov_b32 s4, 0x4200000
	global_store_dwordx4 v[50:51], v[26:29], off
	v_lshl_add_u64 v[22:23], v[34:35], 0, s[18:19]
	v_add_co_u32_e32 v54, vcc, s4, v22
	s_mov_b32 s4, 0x6200000
	s_nop 0
	v_addc_co_u32_e32 v55, vcc, 0, v23, vcc
	v_add_co_u32_e32 v56, vcc, s4, v22
	s_mov_b32 s4, 0xe901000
	s_nop 0
	v_addc_co_u32_e32 v57, vcc, 0, v23, vcc
	global_store_dwordx4 v[54:55], v[14:17], off nt
	global_store_dwordx4 v[54:55], v[18:21], off offset:16 nt
	global_store_dwordx4 v[56:57], v[6:9], off nt
	global_store_dwordx4 v[56:57], v[10:13], off offset:16 nt
	ds_write_b128 v41, v[2:5]
	s_add_u32 s18, s18, 0x1000
	v_add_co_u32_e32 v10, vcc, s4, v36
	s_addc_u32 s19, s19, 0
	s_nop 0
	v_addc_co_u32_e32 v11, vcc, 0, v37, vcc
	global_load_dwordx4 v[2:5], v[10:11], off offset:1024
	global_load_dwordx4 v[6:9], v[10:11], off offset:2048
	s_nop 0
	global_load_dwordx4 v[10:13], v[10:11], off offset:3072
	s_nop 0
	global_load_dwordx4 v[22:25], v[30:31], off offset:16
	global_load_dwordx4 v[26:29], v[30:31], off
	global_load_dwordx4 v[42:45], v[32:33], off offset:16
	global_load_dwordx4 v[46:49], v[32:33], off
	s_add_u32 s16, s16, 0x800
	s_addc_u32 s17, s17, 0
	s_cmpk_eq_i32 s18, 0x4000
	s_waitcnt vmcnt(6)
; DI void qkv_row(const Params& p, const bf16* PROJ, int m, int lane, float* kout, float* vout, u32x4& vraw) {
;     bf16* QB = (bf16*)(p.ws + WS_QB); bf16* KB = (bf16*)(p.ws + WS_KB);
;     const bf16* pr = PROJ + (size_t)m * EVEN_IN;
;     const u32x4 q8 = *(const u32x4*)(pr + 8 * lane), k8 = *(const u32x4*)(pr + SBW + 8 * lane), v8 = *(const u32x4*)(pr + 2 * SBW + 8 * lane);
;     float q[8], k[8], v[8];
; #pragma unroll
;     for (int j = 0; j < 4; ++j) { q[2 * j] = bflo(q8[j]); q[2 * j + 1] = bfhi(q8[j]); k[2 * j] = bflo(k8[j]); k[2 * j + 1] = bfhi(k8[j]); v[2 * j] = bflo(v8[j]); v[2 * j + 1] = bfhi(v8[j]); }
;     float sq = 0.f, sk = 0.f;
; #pragma unroll
;     for (int j = 0; j < 8; ++j) { sq += q[j] * q[j]; sk += k[j] * k[j]; }
; #pragma unroll
;     for (int o = 1; o < 8; o <<= 1) { sq += __shfl_xor(sq, o); sk += __shfl_xor(sk, o); }
;     const float rq = frsq(sq * (1.f / SBD) + EPS) * (0.125f * LOG2E), rk = frsq(sk * (1.f / SBD) + EPS);
;     const float* qg = (const float*)p.in[I_QG] + 8 * (lane & 7); const float* kg = (const float*)p.in[I_KG] + 8 * (lane & 7);
;     const f32x4 qg0 = *(const f32x4*)qg, qg1 = *(const f32x4*)(qg + 4), kg0 = *(const f32x4*)kg, kg1 = *(const f32x4*)(kg + 4);
;     float qn[8], kn[8];
; #pragma unroll
;     for (int j = 0; j < 4; ++j) { qn[j] = q[j] * rq * qg0[j]; qn[4 + j] = q[4 + j] * rq * qg1[j]; kn[j] = k[j] * rk * kg0[j]; kn[4 + j] = k[4 + j] * rk * kg1[j]; }
;     u32x4 qo, ko;
; #pragma unroll
;     for (int j = 0; j < 4; ++j) { qo[j] = pk2(qn[2 * j], qn[2 * j + 1]); ko[j] = pk2(kn[2 * j], kn[2 * j + 1]); }
;     *(u32x4*)(QB + (size_t)m * SBW + 8 * lane) = qo; *(u32x4*)(KB + (size_t)m * SBW + 8 * lane) = ko;
;     *(f32x4*)(kout + 8 * lane) = (f32x4){kn[0], kn[1], kn[2], kn[3]}; *(f32x4*)(kout + 8 * lane + 4) = (f32x4){kn[4], kn[5], kn[6], kn[7]};
;     *(f32x4*)(vout + 8 * lane) = (f32x4){v[0], v[1], v[2], v[3]}; *(f32x4*)(vout + 8 * lane + 4) = (f32x4){v[4], v[5], v[6], v[7]};
;     vraw = v8;
; }
; DI void phase_even_a(const Params& p, LAS unsigned char* lds, int tid, int lane_, int wave, int G) {
;     ...
;             for (int i = 0; i < 8; ++i) { const int tl = wave * 8 + i, m = m0 + tl; u32x4 vraw;
;                 qkv_row(p, PROJ, m, lane, p.out + O_KP + (size_t)m * SBW, p.out + O_VP + (size_t)m * SBW, vraw);
;                 *(LAS u32x4*)(vt + tl * VLD + 8 * lane) = vraw; }
;             __syncthreads();
	v_lshlrev_b32_e32 v204, 16, v2
	v_and_b32_e32 v205, 0xffff0000, v2
	v_lshlrev_b32_e32 v62, 16, v3
	v_and_b32_e32 v63, 0xffff0000, v3
	v_pk_mul_f32 v[2:3], v[204:205], v[204:205]
	v_pk_mul_f32 v[64:65], v[62:63], v[62:63]
	v_add_f32_e32 v2, v2, v3
	v_lshlrev_b32_e32 v60, 16, v4
	v_and_b32_e32 v61, 0xffff0000, v4
	v_add_f32_e32 v2, v64, v2
	v_lshlrev_b32_e32 v36, 16, v5
	v_and_b32_e32 v37, 0xffff0000, v5
	v_pk_mul_f32 v[4:5], v[60:61], v[60:61]
	v_add_f32_e32 v2, v65, v2
	v_add_f32_e32 v2, v4, v2
	v_pk_mul_f32 v[58:59], v[36:37], v[36:37]
	v_add_f32_e32 v2, v5, v2
	v_add_f32_e32 v2, v58, v2
	v_add_f32_e32 v2, v59, v2
	ds_bpermute_b32 v3, v38, v2
	s_waitcnt vmcnt(4)
	v_lshlrev_b32_e32 v14, 16, v10
	v_and_b32_e32 v15, 0xffff0000, v10
	v_lshlrev_b32_e32 v16, 16, v11
	v_and_b32_e32 v17, 0xffff0000, v11
	s_waitcnt lgkmcnt(0)
	v_add_f32_e32 v2, v2, v3
	ds_bpermute_b32 v3, v39, v2
	v_lshlrev_b32_e32 v18, 16, v12
	v_and_b32_e32 v19, 0xffff0000, v12
	v_lshlrev_b32_e32 v20, 16, v13
	v_and_b32_e32 v21, 0xffff0000, v13
	s_waitcnt lgkmcnt(0)
	v_add_f32_e32 v2, v2, v3
	ds_bpermute_b32 v3, v40, v2
	s_waitcnt lgkmcnt(0)
	v_add_f32_e32 v2, v2, v3
	v_fmamk_f32 v2, v2, 0x3c800000, v214
	v_rsq_f32_e32 v2, v2
	s_nop 0
	v_mul_f32_e32 v2, 0x3e38aa3b, v2
	v_pk_mul_f32 v[4:5], v[2:3], v[204:205] op_sel_hi:[0,1]
	s_waitcnt vmcnt(2)
	v_pk_mul_f32 v[26:27], v[26:27], v[4:5]
	v_pk_mul_f32 v[4:5], v[2:3], v[60:61] op_sel_hi:[0,1]
	v_pk_mul_f32 v[58:59], v[22:23], v[4:5]
	v_pk_mul_f32 v[4:5], v[2:3], v[62:63] op_sel_hi:[0,1]
	v_pk_mul_f32 v[2:3], v[2:3], v[36:37] op_sel_hi:[0,1]
	v_lshlrev_b32_e32 v62, 16, v6
	v_and_b32_e32 v63, 0xffff0000, v6
	v_pk_mul_f32 v[36:37], v[24:25], v[2:3]
	v_lshlrev_b32_e32 v24, 16, v7
	v_and_b32_e32 v25, 0xffff0000, v7
	v_pk_mul_f32 v[6:7], v[62:63], v[62:63]
	v_pk_mul_f32 v[60:61], v[24:25], v[24:25]
	v_add_f32_e32 v6, v6, v7
	v_pk_mul_f32 v[28:29], v[28:29], v[4:5]
	v_lshlrev_b32_e32 v4, 16, v8
	v_and_b32_e32 v5, 0xffff0000, v8
	v_add_f32_e32 v6, v60, v6
	v_lshlrev_b32_e32 v22, 16, v9
	v_and_b32_e32 v23, 0xffff0000, v9
	v_pk_mul_f32 v[8:9], v[4:5], v[4:5]
	v_add_f32_e32 v6, v61, v6
	v_add_f32_e32 v6, v8, v6
	v_pk_mul_f32 v[2:3], v[22:23], v[22:23]
	v_add_f32_e32 v6, v9, v6
	v_add_f32_e32 v2, v2, v6
	v_add_f32_e32 v2, v3, v2
	ds_bpermute_b32 v3, v38, v2
	s_waitcnt lgkmcnt(0)
	v_add_f32_e32 v2, v2, v3
	ds_bpermute_b32 v3, v39, v2
	s_waitcnt lgkmcnt(0)
	v_add_f32_e32 v2, v2, v3
	ds_bpermute_b32 v3, v40, v2
	s_waitcnt lgkmcnt(0)
	v_add_f32_e32 v2, v2, v3
	v_fmamk_f32 v2, v2, 0x3c800000, v214
	v_rsq_f32_e32 v8, v2
	s_nop 0
	v_pk_mul_f32 v[4:5], v[8:9], v[4:5] op_sel_hi:[0,1]
	v_pk_mul_f32 v[2:3], v[8:9], v[62:63] op_sel_hi:[0,1]
	s_waitcnt vmcnt(1)
	v_pk_mul_f32 v[6:7], v[42:43], v[4:5]
	v_pk_mul_f32 v[4:5], v[8:9], v[24:25] op_sel_hi:[0,1]
	v_pk_mul_f32 v[8:9], v[8:9], v[22:23] op_sel_hi:[0,1]
	s_waitcnt vmcnt(0)
	v_pk_mul_f32 v[2:3], v[46:47], v[2:3]
	v_pk_mul_f32 v[4:5], v[48:49], v[4:5]
	v_pk_mul_f32 v[8:9], v[44:45], v[8:9]
	v_cvt_pk_bf16_f32 v22, v26, v27
	v_cvt_pk_bf16_f32 v23, v28, v29
	v_cvt_pk_bf16_f32 v24, v58, v59
	v_cvt_pk_bf16_f32 v25, v36, v37
	v_cvt_pk_bf16_f32 v26, v2, v3
	v_cvt_pk_bf16_f32 v27, v4, v5
	v_cvt_pk_bf16_f32 v28, v6, v7
	v_cvt_pk_bf16_f32 v29, v8, v9
	global_store_dwordx4 v[50:51], v[22:25], off offset:1024
	global_store_dwordx4 v[52:53], v[26:29], off offset:1024
	global_store_dwordx4 v[54:55], v[2:5], off offset:2048 nt
	global_store_dwordx4 v[54:55], v[6:9], off offset:2064 nt
	global_store_dwordx4 v[56:57], v[14:17], off offset:2048 nt
	global_store_dwordx4 v[56:57], v[18:21], off offset:2064 nt
	ds_write_b128 v41, v[10:13] offset:1040
	v_add_u32_e32 v41, 0x820, v41
	s_cbranch_scc0 .LBB0_454
	v_lshl_add_u32 v4, v202, 1, 0
	s_waitcnt lgkmcnt(0)
	s_barrier
; DI void phase_even_a(const Params& p, LAS unsigned char* lds, int tid, int lane_, int wave, int G) {
;     ...
;             __syncthreads();
;             { const int col = tidv; bf16* dst = VT + ((size_t)(b * SBH) * SBD + col) * T_P + t0;
; #pragma unroll
;               for (int j = 0; j < 8; ++j) { unsigned w[4];
; #pragma unroll
;                   for (int i = 0; i < 4; ++i) w[i] = (unsigned)vt[(8 * j + 2 * i) * VLD + col] | ((unsigned)vt[(8 * j + 2 * i + 1) * VLD + col] << 16);
;                   *(u32x4*)(dst + 8 * j) = (u32x4){w[0], w[1], w[2], w[3]}; } }
;             __syncthreads();
;             float x0 = 0.f, x1 = 0.f, x2 = 0.f;
;             if (c > 0) { x0 = bf2f(PROJ[(size_t)(m0 - 3) * EVEN_IN + 3 * SBW + ch]); x1 = bf2f(PROJ[(size_t)(m0 - 2) * EVEN_IN + 3 * SBW + ch]); x2 = bf2f(PROJ[(size_t)(m0 - 1) * EVEN_IN + 3 * SBW + ch]); }
	ds_read_u16 v5, v4
	ds_read_u16 v6, v4 offset:1040
	s_lshl_b32 s14, s13, 3
	s_ashr_i32 s15, s14, 31
	s_and_b32 s16, s12, 63
	s_lshl_b64 s[14:15], s[14:15], 19
	s_waitcnt lgkmcnt(0)
	v_lshl_or_b32 v6, v6, 16, v5
	ds_read_u16 v5, v4 offset:2080
	ds_read_u16 v7, v4 offset:3120
	v_ashrrev_i32_e32 v203, 31, v202
	s_add_u32 s14, s23, s14
	s_addc_u32 s15, s34, s15
	v_lshlrev_b64 v[2:3], 13, v[202:203]
	s_waitcnt lgkmcnt(0)
	v_lshl_or_b32 v7, v7, 16, v5
	ds_read_u16 v5, v4 offset:4160
	ds_read_u16 v8, v4 offset:5200
	v_lshl_add_u64 v[2:3], s[14:15], 0, v[2:3]
	s_lshl_b32 s4, s16, 7
	v_lshl_add_u64 v[2:3], v[2:3], 0, s[4:5]
	s_cmp_lg_u32 s16, 0
	s_waitcnt lgkmcnt(0)
	v_lshl_or_b32 v8, v8, 16, v5
	ds_read_u16 v5, v4 offset:6240
	ds_read_u16 v9, v4 offset:7280
	s_waitcnt lgkmcnt(0)
	v_lshl_or_b32 v9, v9, 16, v5
	global_store_dwordx4 v[2:3], v[6:9], off
	ds_read_u16 v5, v4 offset:8320
	ds_read_u16 v6, v4 offset:9360
	s_waitcnt lgkmcnt(0)
	v_lshl_or_b32 v6, v6, 16, v5
	ds_read_u16 v5, v4 offset:10400
	ds_read_u16 v7, v4 offset:11440
	s_waitcnt lgkmcnt(0)
	v_lshl_or_b32 v7, v7, 16, v5
	ds_read_u16 v5, v4 offset:12480
	ds_read_u16 v8, v4 offset:13520
	s_waitcnt lgkmcnt(0)
	v_lshl_or_b32 v8, v8, 16, v5
	ds_read_u16 v5, v4 offset:14560
	ds_read_u16 v9, v4 offset:15600
	s_waitcnt lgkmcnt(0)
	v_lshl_or_b32 v9, v9, 16, v5
	global_store_dwordx4 v[2:3], v[6:9], off offset:16
	ds_read_u16 v5, v4 offset:16640
	ds_read_u16 v6, v4 offset:17680
	s_waitcnt lgkmcnt(0)
	v_lshl_or_b32 v6, v6, 16, v5
	ds_read_u16 v5, v4 offset:18720
	ds_read_u16 v7, v4 offset:19760
	s_waitcnt lgkmcnt(0)
	v_lshl_or_b32 v7, v7, 16, v5
	ds_read_u16 v5, v4 offset:20800
	ds_read_u16 v8, v4 offset:21840
	s_waitcnt lgkmcnt(0)
	v_lshl_or_b32 v8, v8, 16, v5
	ds_read_u16 v5, v4 offset:22880
	ds_read_u16 v9, v4 offset:23920
	s_waitcnt lgkmcnt(0)
	v_lshl_or_b32 v9, v9, 16, v5
	global_store_dwordx4 v[2:3], v[6:9], off offset:32
	ds_read_u16 v5, v4 offset:24960
	ds_read_u16 v6, v4 offset:26000
	s_waitcnt lgkmcnt(0)
	v_lshl_or_b32 v6, v6, 16, v5
	ds_read_u16 v5, v4 offset:27040
	ds_read_u16 v7, v4 offset:28080
	s_waitcnt lgkmcnt(0)
	v_lshl_or_b32 v7, v7, 16, v5
	ds_read_u16 v5, v4 offset:29120
	ds_read_u16 v8, v4 offset:30160
	s_waitcnt lgkmcnt(0)
	v_lshl_or_b32 v8, v8, 16, v5
	ds_read_u16 v5, v4 offset:31200
	ds_read_u16 v9, v4 offset:32240
	s_waitcnt lgkmcnt(0)
	v_lshl_or_b32 v9, v9, 16, v5
	global_store_dwordx4 v[2:3], v[6:9], off offset:48
	ds_read_u16 v5, v4 offset:33280
	ds_read_u16 v6, v4 offset:34320
	s_waitcnt lgkmcnt(0)
	v_lshl_or_b32 v6, v6, 16, v5
	ds_read_u16 v5, v4 offset:35360
	ds_read_u16 v7, v4 offset:36400
	s_waitcnt lgkmcnt(0)
	v_lshl_or_b32 v7, v7, 16, v5
	ds_read_u16 v5, v4 offset:37440
	ds_read_u16 v8, v4 offset:38480
	s_waitcnt lgkmcnt(0)
	v_lshl_or_b32 v8, v8, 16, v5
	ds_read_u16 v5, v4 offset:39520
	ds_read_u16 v9, v4 offset:40560
	s_waitcnt lgkmcnt(0)
	v_lshl_or_b32 v9, v9, 16, v5
	global_store_dwordx4 v[2:3], v[6:9], off offset:64
	ds_read_u16 v5, v4 offset:41600
	ds_read_u16 v6, v4 offset:42640
	s_waitcnt lgkmcnt(0)
	v_lshl_or_b32 v6, v6, 16, v5
	ds_read_u16 v5, v4 offset:43680
	ds_read_u16 v7, v4 offset:44720
	s_waitcnt lgkmcnt(0)
	v_lshl_or_b32 v7, v7, 16, v5
	ds_read_u16 v5, v4 offset:45760
	ds_read_u16 v8, v4 offset:46800
	s_waitcnt lgkmcnt(0)
	v_lshl_or_b32 v8, v8, 16, v5
	ds_read_u16 v5, v4 offset:47840
	ds_read_u16 v9, v4 offset:48880
	s_waitcnt lgkmcnt(0)
	v_lshl_or_b32 v9, v9, 16, v5
	global_store_dwordx4 v[2:3], v[6:9], off offset:80
	ds_read_u16 v5, v4 offset:49920
	ds_read_u16 v6, v4 offset:50960
	s_waitcnt lgkmcnt(0)
	v_lshl_or_b32 v6, v6, 16, v5
	ds_read_u16 v5, v4 offset:52000
	ds_read_u16 v7, v4 offset:53040
	s_waitcnt lgkmcnt(0)
	v_lshl_or_b32 v7, v7, 16, v5
	ds_read_u16 v5, v4 offset:54080
	ds_read_u16 v8, v4 offset:55120
	s_waitcnt lgkmcnt(0)
	v_lshl_or_b32 v8, v8, 16, v5
	ds_read_u16 v5, v4 offset:56160
	ds_read_u16 v9, v4 offset:57200
	s_waitcnt lgkmcnt(0)
	v_lshl_or_b32 v9, v9, 16, v5
	global_store_dwordx4 v[2:3], v[6:9], off offset:96
	ds_read_u16 v5, v4 offset:58240
	ds_read_u16 v6, v4 offset:59280
	s_waitcnt lgkmcnt(0)
	v_lshl_or_b32 v6, v6, 16, v5
	ds_read_u16 v5, v4 offset:60320
	ds_read_u16 v7, v4 offset:61360
	s_waitcnt lgkmcnt(0)
	v_lshl_or_b32 v7, v7, 16, v5
	ds_read_u16 v5, v4 offset:62400
	ds_read_u16 v8, v4 offset:63440
	s_waitcnt lgkmcnt(0)
	v_lshl_or_b32 v8, v8, 16, v5
	ds_read_u16 v5, v4 offset:64480
	ds_read_u16 v9, v4 offset:65520
	s_waitcnt lgkmcnt(0)
	v_lshl_or_b32 v9, v9, 16, v5
	global_store_dwordx4 v[2:3], v[6:9], off offset:112
	v_lshlrev_b64 v[2:3], 1, v[202:203]
	s_barrier
	s_cbranch_scc0 .LBB0_457
	s_lshl_b32 s4, s16, 6
	s_or_b32 s4, s21, s4
	s_mul_i32 s17, s4, 0x1400
	s_add_i32 s14, s4, -3
	s_mul_hi_i32 s15, s14, 0x1400
	s_add_i32 s14, s17, 0xffffc400
	v_readlane_b32 s18, v243, 6
	v_readlane_b32 s19, v243, 7
	s_add_u32 s14, s18, s14
	s_addc_u32 s15, s19, s15
	v_lshl_add_u64 v[6:7], s[14:15], 0, v[2:3]
	s_add_i32 s14, s4, -2
	s_mul_hi_i32 s15, s14, 0x1400
	s_add_i32 s14, s17, 0xffffd800
	s_add_u32 s14, s18, s14
	s_addc_u32 s15, s19, s15
	v_lshl_add_u64 v[8:9], s[14:15], 0, v[2:3]
	global_load_ushort v5, v[6:7], off offset:3072
	s_nop 0
	global_load_ushort v6, v[8:9], off offset:3072
	s_add_i32 s4, s4, -1
	s_addk_i32 s17, 0xec00
	s_mul_hi_i32 s4, s4, 0x1400
	s_add_u32 s14, s18, s17
	s_addc_u32 s15, s19, s4
	v_lshl_add_u64 v[8:9], s[14:15], 0, v[2:3]
	s_waitcnt vmcnt(0)
	v_lshlrev_b32_e32 v7, 16, v6
	v_lshlrev_b32_e32 v6, 16, v5
	global_load_ushort v5, v[8:9], off offset:3072
	s_waitcnt vmcnt(0)
	v_lshlrev_b32_e32 v9, 16, v5
	s_branch .LBB0_458

; DI void qkv_row(const Params& p, const bf16* PROJ, int m, int lane, float* kout, float* vout, u32x4& vraw) {
;     bf16* QB = (bf16*)(p.ws + WS_QB); bf16* KB = (bf16*)(p.ws + WS_KB);
;     const bf16* pr = PROJ + (size_t)m * EVEN_IN;
;     const u32x4 q8 = *(const u32x4*)(pr + 8 * lane), k8 = *(const u32x4*)(pr + SBW + 8 * lane), v8 = *(const u32x4*)(pr + 2 * SBW + 8 * lane);
;     float q[8], k[8], v[8];
; #pragma unroll
;     for (int j = 0; j < 4; ++j) { q[2 * j] = bflo(q8[j]); q[2 * j + 1] = bfhi(q8[j]); k[2 * j] = bflo(k8[j]); k[2 * j + 1] = bfhi(k8[j]); v[2 * j] = bflo(v8[j]); v[2 * j + 1] = bfhi(v8[j]); }
;     float sq = 0.f, sk = 0.f;
; #pragma unroll
;     for (int j = 0; j < 8; ++j) { sq += q[j] * q[j]; sk += k[j] * k[j]; }
; #pragma unroll
;     for (int o = 1; o < 8; o <<= 1) { sq += __shfl_xor(sq, o); sk += __shfl_xor(sk, o); }
;     const float rq = frsq(sq * (1.f / SBD) + EPS) * (0.125f * LOG2E), rk = frsq(sk * (1.f / SBD) + EPS);
;     const float* qg = (const float*)p.in[I_QG] + 8 * (lane & 7); const float* kg = (const float*)p.in[I_KG] + 8 * (lane & 7);
;     const f32x4 qg0 = *(const f32x4*)qg, qg1 = *(const f32x4*)(qg + 4), kg0 = *(const f32x4*)kg, kg1 = *(const f32x4*)(kg + 4);
;     float qn[8], kn[8];
; #pragma unroll
;     for (int j = 0; j < 4; ++j) { qn[j] = q[j] * rq * qg0[j]; qn[4 + j] = q[4 + j] * rq * qg1[j]; kn[j] = k[j] * rk * kg0[j]; kn[4 + j] = k[4 + j] * rk * kg1[j]; }
;     u32x4 qo, ko;
; #pragma unroll
;     for (int j = 0; j < 4; ++j) { qo[j] = pk2(qn[2 * j], qn[2 * j + 1]); ko[j] = pk2(kn[2 * j], kn[2 * j + 1]); }
;     *(u32x4*)(QB + (size_t)m * SBW + 8 * lane) = qo; *(u32x4*)(KB + (size_t)m * SBW + 8 * lane) = ko;
;     *(f32x4*)(kout + 8 * lane) = (f32x4){kn[0], kn[1], kn[2], kn[3]}; *(f32x4*)(kout + 8 * lane + 4) = (f32x4){kn[4], kn[5], kn[6], kn[7]};
; DI void phase_even_a(const Params& p, LAS unsigned char* lds, int tid, int lane_, int wave, int G) {
;     ...
;             const int s = unit - NB_P * 64, m0 = MP + 4 * s;
;             int chs = tid; asm volatile("" : "+v"(chs)); const int lane = chs & 63;
;             if (wave < 4) { const int m = m0 + wave; u32x4 vraw;
;                 qkv_row(p, PROJ, m, lane, p.out + O_KS + (size_t)(4 * s + wave) * SBW, p.out + O_VS + (size_t)(4 * s + wave) * SBW, vraw);
;                 *(u32x4*)(VS + (size_t)(4 * s + wave) * SBW + 8 * lane) = vraw; }
.LBB0_469:
	s_and_b64 vcc, exec, s[14:15]
	s_cbranch_vccz .LBB0_451
	s_add_i32 s4, s12, 0xffffff00
	s_lshl_b32 s14, s4, 2
	s_add_i32 s13, s14, 0x4000
	v_mov_b32_e32 v202, v0
	s_andn2_b64 vcc, exec, s[6:7]
	s_cbranch_vccnz .LBB0_472
	s_or_b32 s14, s14, s90
	s_mov_b32 s15, s5
	s_or_b32 s20, s13, s90
	s_lshl_b64 s[16:17], s[14:15], 11
	s_add_u32 s18, s44, s16
	s_addc_u32 s19, s45, s17
	s_add_u32 s16, s46, s16
	s_addc_u32 s17, s47, s17
	s_mul_i32 s60, s20, 0x1400
	v_readlane_b32 s24, v243, 6
	v_lshlrev_b32_e32 v2, 3, v202
	s_mul_hi_u32 s21, s20, 0x1400
	v_readlane_b32 s25, v243, 7
	s_add_u32 s60, s24, s60
	v_and_b32_e32 v54, 0x1f8, v2
	s_addc_u32 s61, s25, s21
	v_lshlrev_b32_e32 v55, 1, v54
	global_load_dwordx4 v[6:9], v55, s[60:61]
	global_load_dwordx4 v[10:13], v55, s[60:61] offset:1024
	global_load_dwordx4 v[2:5], v55, s[60:61] offset:2048
	v_readlane_b32 s72, v244, 43
	v_and_b32_e32 v14, 64, v216
	v_readlane_b32 s73, v244, 44
	v_xor_b32_e32 v15, 1, v216
	v_lshlrev_b32_e32 v16, 5, v202
	v_add_u32_e32 v57, 64, v14
	v_readlane_b32 s74, v244, 45
	v_readlane_b32 s75, v244, 46
	v_readlane_b32 s76, v244, 47
	v_readlane_b32 s77, v244, 48
	v_readlane_b32 s78, v244, 49
	v_readlane_b32 s79, v244, 50
	s_mov_b64 s[60:61], s[72:73]
	v_and_b32_e32 v26, 0xe0, v16
	v_cmp_lt_i32_e32 vcc, v15, v57
	s_mov_b64 s[62:63], s[74:75]
	s_mov_b64 s[64:65], s[76:77]
	v_cndmask_b32_e32 v31, v216, v15, vcc
	global_load_dwordx4 v[14:17], v26, s[62:63]
	global_load_dwordx4 v[18:21], v26, s[64:65]
	global_load_dwordx4 v[22:25], v26, s[62:63] offset:16
	s_nop 0
	global_load_dwordx4 v[26:29], v26, s[64:65] offset:16
	v_xor_b32_e32 v30, 2, v216
	v_cmp_lt_i32_e32 vcc, v30, v57
	v_lshlrev_b32_e32 v59, 2, v31
	v_xor_b32_e32 v56, 4, v216
	v_cndmask_b32_e32 v58, v216, v30, vcc
	v_cmp_lt_i32_e32 vcc, v56, v57
	s_mov_b32 s21, s5
	s_lshl_b64 s[20:21], s[20:21], 10
	s_add_u32 s60, s40, s20
	s_addc_u32 s61, s41, s21
	s_add_u32 s20, s38, s20
	s_addc_u32 s21, s39, s21
	s_lshl_b64 s[14:15], s[14:15], 10
	s_add_u32 s14, s2, s14
	s_addc_u32 s15, s3, s15
	v_readlane_b32 s80, v244, 51
	v_readlane_b32 s81, v244, 52
	v_readlane_b32 s82, v244, 53
	v_readlane_b32 s83, v244, 54
	v_readlane_b32 s84, v244, 55
	v_readlane_b32 s85, v244, 56
	v_readlane_b32 s86, v244, 57
	v_readlane_b32 s87, v244, 58
	s_mov_b64 s[66:67], s[78:79]
	s_waitcnt vmcnt(6)
	v_lshlrev_b32_e32 v36, 16, v6
	v_and_b32_e32 v37, 0xffff0000, v6
	s_waitcnt vmcnt(5)
	v_lshlrev_b32_e32 v44, 16, v10
	v_and_b32_e32 v45, 0xffff0000, v10
	v_lshlrev_b32_e32 v34, 16, v7
	v_and_b32_e32 v35, 0xffff0000, v7
	v_lshlrev_b32_e32 v38, 16, v13
	v_and_b32_e32 v39, 0xffff0000, v13
	v_lshlrev_b32_e32 v40, 16, v12
	v_and_b32_e32 v41, 0xffff0000, v12
	v_lshlrev_b32_e32 v42, 16, v11
	v_and_b32_e32 v43, 0xffff0000, v11
	v_pk_mul_f32 v[12:13], v[36:37], v[36:37]
	v_pk_mul_f32 v[52:53], v[44:45], v[44:45]
	v_pk_mul_f32 v[10:11], v[34:35], v[34:35]
	v_pk_mul_f32 v[50:51], v[42:43], v[42:43]
	v_add_f32_e32 v12, v12, v13
	v_add_f32_e32 v13, v52, v53
	v_lshlrev_b32_e32 v32, 16, v8
	v_and_b32_e32 v33, 0xffff0000, v8
	v_add_f32_e32 v10, v10, v12
	v_add_f32_e32 v12, v50, v13
	v_lshlrev_b32_e32 v30, 16, v9
	v_and_b32_e32 v31, 0xffff0000, v9
	v_pk_mul_f32 v[8:9], v[32:33], v[32:33]
	v_pk_mul_f32 v[48:49], v[40:41], v[40:41]
	v_add_f32_e32 v10, v11, v10
	v_add_f32_e32 v11, v51, v12
	v_add_f32_e32 v8, v8, v10
	v_add_f32_e32 v10, v48, v11
	v_pk_mul_f32 v[6:7], v[30:31], v[30:31]
	v_pk_mul_f32 v[46:47], v[38:39], v[38:39]
	v_add_f32_e32 v8, v9, v8
	v_add_f32_e32 v9, v49, v10
	v_add_f32_e32 v6, v6, v8
	v_add_f32_e32 v8, v46, v9
	v_add_f32_e32 v6, v7, v6
	v_add_f32_e32 v7, v47, v8
	ds_bpermute_b32 v8, v59, v6
	ds_bpermute_b32 v9, v59, v7
	v_lshlrev_b32_e32 v11, 2, v58
	v_cndmask_b32_e32 v10, v216, v56, vcc
	v_lshlrev_b32_e32 v10, 2, v10
	s_waitcnt lgkmcnt(1)
	v_add_f32_e32 v12, v6, v8
	s_waitcnt lgkmcnt(0)
	v_add_f32_e32 v9, v7, v9
	ds_bpermute_b32 v13, v11, v12
	ds_bpermute_b32 v11, v11, v9
	s_waitcnt vmcnt(4)
	v_lshlrev_b32_e32 v6, 16, v2
	v_and_b32_e32 v7, 0xffff0000, v2
	v_lshlrev_b32_e32 v8, 16, v3
	s_waitcnt lgkmcnt(1)
	v_add_f32_e32 v12, v12, v13
	s_waitcnt lgkmcnt(0)
	v_add_f32_e32 v13, v9, v11
	ds_bpermute_b32 v46, v10, v12
	ds_bpermute_b32 v47, v10, v13
	v_and_b32_e32 v9, 0xffff0000, v3
	v_lshlrev_b32_e32 v10, 16, v4
	v_and_b32_e32 v11, 0xffff0000, v4
	s_waitcnt lgkmcnt(1)
	v_add_f32_e32 v12, v12, v46
	s_waitcnt lgkmcnt(0)
	v_add_f32_e32 v13, v13, v47
	v_fmamk_f32 v12, v12, 0x3c800000, v214
	v_fmamk_f32 v13, v13, 0x3c800000, v214
	v_rsq_f32_e32 v47, v12
	v_rsq_f32_e32 v46, v13
	v_lshlrev_b32_e32 v12, 16, v5
	v_and_b32_e32 v13, 0xffff0000, v5
	v_mul_f32_e32 v48, 0x3e38aa3b, v47
	v_pk_mul_f32 v[44:45], v[46:47], v[44:45] op_sel_hi:[0,1]
	v_pk_mul_f32 v[40:41], v[46:47], v[40:41] op_sel_hi:[0,1]
	v_pk_mul_f32 v[42:43], v[46:47], v[42:43] op_sel_hi:[0,1]
	v_pk_mul_f32 v[38:39], v[46:47], v[38:39] op_sel_hi:[0,1]
	v_pk_mul_f32 v[36:37], v[48:49], v[36:37] op_sel_hi:[0,1]
	v_pk_mul_f32 v[32:33], v[48:49], v[32:33] op_sel_hi:[0,1]
	v_pk_mul_f32 v[34:35], v[48:49], v[34:35] op_sel_hi:[0,1]
	v_pk_mul_f32 v[30:31], v[48:49], v[30:31] op_sel_hi:[0,1]
	s_waitcnt vmcnt(2)
	v_pk_mul_f32 v[18:19], v[18:19], v[44:45]
	s_waitcnt vmcnt(0)
	v_pk_mul_f32 v[26:27], v[26:27], v[40:41]
	v_pk_mul_f32 v[20:21], v[20:21], v[42:43]
	v_pk_mul_f32 v[28:29], v[28:29], v[38:39]
	v_pk_mul_f32 v[36:37], v[14:15], v[36:37]
	v_pk_mul_f32 v[32:33], v[22:23], v[32:33]
	v_pk_mul_f32 v[34:35], v[16:17], v[34:35]
	v_pk_mul_f32 v[30:31], v[24:25], v[30:31]
	v_cvt_pk_bf16_f32 v14, v18, v19
	v_cvt_pk_bf16_f32 v15, v20, v21
	v_cvt_pk_bf16_f32 v16, v26, v27
	v_cvt_pk_bf16_f32 v17, v28, v29
	v_cvt_pk_bf16_f32 v22, v36, v37
	v_cvt_pk_bf16_f32 v23, v34, v35
	v_cvt_pk_bf16_f32 v24, v32, v33
	v_cvt_pk_bf16_f32 v25, v30, v31
	global_store_dwordx4 v55, v[14:17], s[20:21]
	global_store_dwordx4 v55, v[22:25], s[60:61]
	s_nop 0
	v_lshlrev_b32_e32 v14, 2, v54
	global_store_dwordx4 v14, v[18:21], s[18:19] nt
	global_store_dwordx4 v14, v[26:29], s[18:19] offset:16 nt
	global_store_dwordx4 v14, v[6:9], s[16:17] nt
	global_store_dwordx4 v14, v[10:13], s[16:17] offset:16 nt
	global_store_dwordx4 v55, v[2:5], s[14:15]

; __device__ __forceinline__ unsigned xb_ld(unsigned* p)              { return __hip_atomic_load(p, __ATOMIC_RELAXED, __HIP_MEMORY_SCOPE_AGENT); }
; __device__ __forceinline__ unsigned xb_add(unsigned* p, unsigned v) { return __hip_atomic_fetch_add(p, v, __ATOMIC_RELAXED, __HIP_MEMORY_SCOPE_AGENT); }
; #define XB_SPIN(cond, bar) do { unsigned _sp = 0; while (cond) { __builtin_amdgcn_s_sleep(1); \
;     if ((++_sp & 255u) == 0u) { if (xb_ld(&(bar)[XB_TMO])) break; if (_sp > XB_SPIN_CAP) { atomicAdd(&(bar)[XB_TMO], 1u); break; } } } } while (0)
; __device__ __forceinline__ void xcd_barrier(const XcdBarrier& b) {
;     ...
;         const unsigned old = xb_add(&bar[XB_XSUB(b.x)], 1u);
;         const unsigned gen = old / nloc;
;         if (old + 1u == (gen + 1u) * nloc) {
;             __builtin_amdgcn_fence(__ATOMIC_RELEASE, "agent");
;             asm volatile("s_waitcnt vmcnt(0)" ::: "memory");
;             const unsigned og = xb_add(&bar[XB_TOP], 1u);
;             const unsigned tg = og / nx;
;             if (og + 1u == (tg + 1u) * nx) xb_add(&bar[XB_TOPGEN], 1u);
;             else XB_SPIN(xb_ld(&bar[XB_TOPGEN]) == tg, bar);
;             __builtin_amdgcn_fence(__ATOMIC_ACQUIRE, "agent");
;             xb_add(&bar[XB_XGEN(b.x)], 1u);
;             asm volatile("s_waitcnt vmcnt(0)" ::: "memory");
;         } else {
;             XB_SPIN(xb_ld(&bar[XB_XGEN(b.x)]) == gen, bar);
.LBB0_495:
	s_lshl_b32 s2, s97, 8
	s_add_u32 s6, s94, s2
	s_addc_u32 s7, s95, 0
	v_mov_b32_e32 v2, 0x1000
	v_mov_b32_e32 v4, 1
	global_atomic_add v4, v2, v4, s[6:7] offset:1024 sc0
	v_cvt_f32_u32_e32 v2, v3
	v_sub_u32_e32 v5, 0, v3
	v_rcp_iflag_f32_e32 v2, v2
	s_nop 0
	v_mul_f32_e32 v2, 0x4f7ffffe, v2
	v_cvt_u32_f32_e32 v2, v2
	v_mul_lo_u32 v5, v5, v2
	v_mul_hi_u32 v5, v2, v5
	v_add_u32_e32 v2, v2, v5
	s_waitcnt vmcnt(0)
	v_mul_hi_u32 v2, v4, v2
	v_mul_lo_u32 v5, v2, v3
	v_sub_u32_e32 v5, v4, v5
	v_add_u32_e32 v6, 1, v2
	v_cmp_ge_u32_e32 vcc, v5, v3
	v_add_u32_e32 v4, 1, v4
	s_nop 0
	v_cndmask_b32_e32 v2, v2, v6, vcc
	v_sub_u32_e32 v6, v5, v3
	v_cndmask_b32_e32 v5, v5, v6, vcc
	v_add_u32_e32 v6, 1, v2
	v_cmp_ge_u32_e32 vcc, v5, v3
	s_nop 1
	v_cndmask_b32_e32 v2, v2, v6, vcc
	v_mul_lo_u32 v5, v3, v2
	v_add_u32_e32 v3, v5, v3
	v_cmp_ne_u32_e32 vcc, v4, v3
	s_and_saveexec_b64 s[2:3], vcc
	s_xor_b64 s[8:9], exec, s[2:3]
	s_cbranch_execz .LBB0_509
	s_waitcnt lgkmcnt(0)
	buffer_inv sc1
	v_mov_b32_e32 v1, 0x2000
	global_load_dword v1, v1, s[6:7] offset:1024 sc1
	s_add_u32 s14, s6, 0x2400
	s_addc_u32 s15, s7, 0
	s_waitcnt vmcnt(0)
	v_cmp_eq_u32_e32 vcc, v1, v2
	s_and_saveexec_b64 s[10:11], vcc
	s_cbranch_execz .LBB0_508
	v_readlane_b32 s16, v244, 3
	v_readlane_b32 s22, v244, 9
	v_readlane_b32 s17, v244, 4
	v_readlane_b32 s23, v244, 10
	s_add_u32 s12, s22, 0x4200
	v_readlane_b32 s18, v244, 5
	v_readlane_b32 s19, v244, 6
	s_addc_u32 s13, s23, 0
	s_mov_b32 s2, 1
	s_mov_b64 s[16:17], 0
	v_mov_b32_e32 v1, 0
	v_readlane_b32 s20, v244, 7
	v_readlane_b32 s21, v244, 8
	s_branch .LBB0_499

; __device__ __forceinline__ unsigned xb_ld(unsigned* p)              { return __hip_atomic_load(p, __ATOMIC_RELAXED, __HIP_MEMORY_SCOPE_AGENT); }
; #define XB_SPIN(cond, bar) do { unsigned _sp = 0; while (cond) { __builtin_amdgcn_s_sleep(1); \
;     if ((++_sp & 255u) == 0u) { if (xb_ld(&(bar)[XB_TMO])) break; if (_sp > XB_SPIN_CAP) { atomicAdd(&(bar)[XB_TMO], 1u); break; } } } } while (0)
; __device__ __forceinline__ void xcd_barrier(const XcdBarrier& b) {
;     ...
;             XB_SPIN(xb_ld(&bar[XB_XGEN(b.x)]) == gen, bar);
;             __builtin_amdgcn_fence(__ATOMIC_ACQUIRE, "agent");
;             asm volatile("s_waitcnt vmcnt(0)" ::: "memory");
.LBB0_508:
	s_or_b64 exec, exec, s[10:11]
	s_waitcnt vmcnt(0)
	s_waitcnt vmcnt(0)

; __device__ __forceinline__ unsigned xb_ld(unsigned* p)              { return __hip_atomic_load(p, __ATOMIC_RELAXED, __HIP_MEMORY_SCOPE_AGENT); }
; __device__ __forceinline__ unsigned xb_add(unsigned* p, unsigned v) { return __hip_atomic_fetch_add(p, v, __ATOMIC_RELAXED, __HIP_MEMORY_SCOPE_AGENT); }
; #define XB_SPIN(cond, bar) do { unsigned _sp = 0; while (cond) { __builtin_amdgcn_s_sleep(1); \
;     if ((++_sp & 255u) == 0u) { if (xb_ld(&(bar)[XB_TMO])) break; if (_sp > XB_SPIN_CAP) { atomicAdd(&(bar)[XB_TMO], 1u); break; } } } } while (0)
; __device__ __forceinline__ void xcd_barrier(const XcdBarrier& b) {
;     ...
;         const unsigned old = xb_add(&bar[XB_XSUB(b.x)], 1u);
;         const unsigned gen = old / nloc;
;         if (old + 1u == (gen + 1u) * nloc) {
;             __builtin_amdgcn_fence(__ATOMIC_RELEASE, "agent");
;             asm volatile("s_waitcnt vmcnt(0)" ::: "memory");
;             const unsigned og = xb_add(&bar[XB_TOP], 1u);
;             const unsigned tg = og / nx;
;             if (og + 1u == (tg + 1u) * nx) xb_add(&bar[XB_TOPGEN], 1u);
;             else XB_SPIN(xb_ld(&bar[XB_TOPGEN]) == tg, bar);
;             __builtin_amdgcn_fence(__ATOMIC_ACQUIRE, "agent");
;             xb_add(&bar[XB_XGEN(b.x)], 1u);
;             asm volatile("s_waitcnt vmcnt(0)" ::: "memory");
;         } else {
;             XB_SPIN(xb_ld(&bar[XB_XGEN(b.x)]) == gen, bar);
.LBB0_755:
	s_lshl_b32 s2, s97, 8
	s_add_u32 s4, s94, s2
	s_addc_u32 s5, s95, 0
	v_mov_b32_e32 v2, 0x1000
	v_mov_b32_e32 v4, 1
	global_atomic_add v4, v2, v4, s[4:5] offset:1024 sc0
	v_cvt_f32_u32_e32 v2, v3
	v_sub_u32_e32 v5, 0, v3
	v_rcp_iflag_f32_e32 v2, v2
	s_nop 0
	v_mul_f32_e32 v2, 0x4f7ffffe, v2
	v_cvt_u32_f32_e32 v2, v2
	v_mul_lo_u32 v5, v5, v2
	v_mul_hi_u32 v5, v2, v5
	v_add_u32_e32 v2, v2, v5
	s_waitcnt vmcnt(0)
	v_mul_hi_u32 v2, v4, v2
	v_mul_lo_u32 v5, v2, v3
	v_sub_u32_e32 v5, v4, v5
	v_add_u32_e32 v6, 1, v2
	v_cmp_ge_u32_e32 vcc, v5, v3
	v_add_u32_e32 v4, 1, v4
	s_nop 0
	v_cndmask_b32_e32 v2, v2, v6, vcc
	v_sub_u32_e32 v6, v5, v3
	v_cndmask_b32_e32 v5, v5, v6, vcc
	v_add_u32_e32 v6, 1, v2
	v_cmp_ge_u32_e32 vcc, v5, v3
	s_nop 1
	v_cndmask_b32_e32 v2, v2, v6, vcc
	v_mul_lo_u32 v5, v3, v2
	v_add_u32_e32 v3, v5, v3
	v_cmp_ne_u32_e32 vcc, v4, v3
	s_and_saveexec_b64 s[2:3], vcc
	s_xor_b64 s[6:7], exec, s[2:3]
	s_cbranch_execz .LBB0_769
	s_waitcnt lgkmcnt(0)
	buffer_inv sc1
	v_mov_b32_e32 v1, 0x2000
	global_load_dword v1, v1, s[4:5] offset:1024 sc1
	s_add_u32 s12, s4, 0x2400
	s_addc_u32 s13, s5, 0
	s_waitcnt vmcnt(0)
	v_cmp_eq_u32_e32 vcc, v1, v2
	s_and_saveexec_b64 s[8:9], vcc
	s_cbranch_execz .LBB0_768
	v_readlane_b32 s16, v244, 3
	v_readlane_b32 s22, v244, 9
	v_readlane_b32 s23, v244, 10
	s_add_u32 s10, s22, 0x4200
	v_readlane_b32 s17, v244, 4
	s_addc_u32 s11, s23, 0
	s_mov_b32 s2, 1
	s_mov_b64 s[14:15], 0
	v_mov_b32_e32 v1, 0
	v_readlane_b32 s18, v244, 5
	v_readlane_b32 s19, v244, 6
	v_readlane_b32 s20, v244, 7
	v_readlane_b32 s21, v244, 8
	s_branch .LBB0_759

; __device__ __forceinline__ unsigned xb_ld(unsigned* p)              { return __hip_atomic_load(p, __ATOMIC_RELAXED, __HIP_MEMORY_SCOPE_AGENT); }
; #define XB_SPIN(cond, bar) do { unsigned _sp = 0; while (cond) { __builtin_amdgcn_s_sleep(1); \
;     if ((++_sp & 255u) == 0u) { if (xb_ld(&(bar)[XB_TMO])) break; if (_sp > XB_SPIN_CAP) { atomicAdd(&(bar)[XB_TMO], 1u); break; } } } } while (0)
; __device__ __forceinline__ void xcd_barrier(const XcdBarrier& b) {
;     ...
;             XB_SPIN(xb_ld(&bar[XB_XGEN(b.x)]) == gen, bar);
;             __builtin_amdgcn_fence(__ATOMIC_ACQUIRE, "agent");
;             asm volatile("s_waitcnt vmcnt(0)" ::: "memory");
.LBB0_768:
	s_or_b64 exec, exec, s[8:9]
	s_waitcnt vmcnt(0)
	s_waitcnt vmcnt(0)

; __device__ __forceinline__ unsigned xb_ld(unsigned* p)              { return __hip_atomic_load(p, __ATOMIC_RELAXED, __HIP_MEMORY_SCOPE_AGENT); }
; __device__ __forceinline__ unsigned xb_add(unsigned* p, unsigned v) { return __hip_atomic_fetch_add(p, v, __ATOMIC_RELAXED, __HIP_MEMORY_SCOPE_AGENT); }
; #define XB_SPIN(cond, bar) do { unsigned _sp = 0; while (cond) { __builtin_amdgcn_s_sleep(1); \
;     if ((++_sp & 255u) == 0u) { if (xb_ld(&(bar)[XB_TMO])) break; if (_sp > XB_SPIN_CAP) { atomicAdd(&(bar)[XB_TMO], 1u); break; } } } } while (0)
; __device__ __forceinline__ void xcd_barrier(const XcdBarrier& b) {
;     ...
;         const unsigned old = xb_add(&bar[XB_XSUB(b.x)], 1u);
;         const unsigned gen = old / nloc;
;         if (old + 1u == (gen + 1u) * nloc) {
;             __builtin_amdgcn_fence(__ATOMIC_RELEASE, "agent");
;             asm volatile("s_waitcnt vmcnt(0)" ::: "memory");
;             const unsigned og = xb_add(&bar[XB_TOP], 1u);
;             const unsigned tg = og / nx;
;             if (og + 1u == (tg + 1u) * nx) xb_add(&bar[XB_TOPGEN], 1u);
;             else XB_SPIN(xb_ld(&bar[XB_TOPGEN]) == tg, bar);
;             __builtin_amdgcn_fence(__ATOMIC_ACQUIRE, "agent");
;             xb_add(&bar[XB_XGEN(b.x)], 1u);
;             asm volatile("s_waitcnt vmcnt(0)" ::: "memory");
;         } else {
;             XB_SPIN(xb_ld(&bar[XB_XGEN(b.x)]) == gen, bar);
.LBB0_1841:
	s_lshl_b32 s2, s97, 8
	s_add_u32 s6, s94, s2
	s_addc_u32 s7, s95, 0
	v_mov_b32_e32 v2, 0x1000
	v_mov_b32_e32 v4, 1
	global_atomic_add v4, v2, v4, s[6:7] offset:1024 sc0
	v_cvt_f32_u32_e32 v2, v3
	v_sub_u32_e32 v5, 0, v3
	v_rcp_iflag_f32_e32 v2, v2
	s_nop 0
	v_mul_f32_e32 v2, 0x4f7ffffe, v2
	v_cvt_u32_f32_e32 v2, v2
	v_mul_lo_u32 v5, v5, v2
	v_mul_hi_u32 v5, v2, v5
	v_add_u32_e32 v2, v2, v5
	s_waitcnt vmcnt(0)
	v_mul_hi_u32 v2, v4, v2
	v_mul_lo_u32 v5, v2, v3
	v_sub_u32_e32 v5, v4, v5
	v_add_u32_e32 v6, 1, v2
	v_cmp_ge_u32_e32 vcc, v5, v3
	v_add_u32_e32 v4, 1, v4
	s_nop 0
	v_cndmask_b32_e32 v2, v2, v6, vcc
	v_sub_u32_e32 v6, v5, v3
	v_cndmask_b32_e32 v5, v5, v6, vcc
	v_add_u32_e32 v6, 1, v2
	v_cmp_ge_u32_e32 vcc, v5, v3
	s_nop 1
	v_cndmask_b32_e32 v2, v2, v6, vcc
	v_mul_lo_u32 v5, v3, v2
	v_add_u32_e32 v3, v5, v3
	v_cmp_ne_u32_e32 vcc, v4, v3
	s_and_saveexec_b64 s[2:3], vcc
	s_xor_b64 s[8:9], exec, s[2:3]
	s_cbranch_execz .LBB0_1855
	s_waitcnt lgkmcnt(0)
	buffer_inv sc1
	v_mov_b32_e32 v1, 0x2000
	global_load_dword v1, v1, s[6:7] offset:1024 sc1
	s_add_u32 s14, s6, 0x2400
	s_addc_u32 s15, s7, 0
	s_waitcnt vmcnt(0)
	v_cmp_eq_u32_e32 vcc, v1, v2
	s_and_saveexec_b64 s[10:11], vcc
	s_cbranch_execz .LBB0_1854
	v_readlane_b32 s16, v244, 3
	v_readlane_b32 s17, v244, 4
	v_readlane_b32 s18, v244, 5
	v_readlane_b32 s19, v244, 6
	v_readlane_b32 s20, v244, 7
	v_readlane_b32 s21, v244, 8
	v_readlane_b32 s22, v244, 9
	v_readlane_b32 s23, v244, 10
	s_mov_b64 s[16:17], s[20:21]
	s_mov_b64 s[18:19], s[22:23]
	s_add_u32 s12, s18, 0x4200
	s_addc_u32 s13, s19, 0
	s_mov_b32 s2, 1
	s_mov_b64 s[16:17], 0
	v_mov_b32_e32 v1, 0
	s_branch .LBB0_1845

; DI unsigned pk2(float lo, float hi) { f32x2 v = {lo, hi}; return __builtin_bit_cast(unsigned, __builtin_convertvector(v, bf16v2)); }
; DI void ssq_add(float* ssq, int row, float s) { atomicAdd((unsigned*)ssq + row, (unsigned)(s * 1024.f + 0.5f)); }
;     __device__ __forceinline__ void operator()(const f32x4 (&acc)[2][2][4][2], const Unit& u, int wr, int wc, int fr, int fq, const Pre&) const {
;         const int row0 = u.pm * BM + wr * 64 + fr, col0 = u.pn * BM + wc * 32 + 8 * fq;
; #pragma unroll
;         for (int ai = 0; ai < 2; ++ai)
; #pragma unroll
;             for (int m = 0; m < 4; ++m) {
;                 const int row = row0 + ai * HALF + m * 16; const size_t off = (size_t)row * DM + col0; float s = 0.f;
; #pragma unroll
;                 for (int bj = 0; bj < 2; ++bj) {
;                     f32x4 b0, b1;
;                     if (BASE_F32) { const float* bp = (const float*)base + off + bj * HALF; b0 = *(const f32x4*)bp; b1 = *(const f32x4*)(bp + 4); }
;                     else { const u32x4 w = *(const u32x4*)((const bf16_t*)base + off + bj * HALF); b0 = (f32x4){bflo(w.x), bfhi(w.x), bflo(w.y), bfhi(w.y)}; b1 = (f32x4){bflo(w.z), bfhi(w.z), bflo(w.w), bfhi(w.w)}; }
;                     const f32x4 o0 = b0 + acc[ai][bj][m][0] * alpha, o1 = b1 + acc[ai][bj][m][1] * alpha;
;                     if (OUT_F32) { float* op = (float*)out + off + bj * HALF; *(f32x4*)op = o0; *(f32x4*)(op + 4) = o1; }
;                     else { u32x4 w; w.x = pk2(o0[0], o0[1]); w.y = pk2(o0[2], o0[3]); w.z = pk2(o1[0], o1[1]); w.w = pk2(o1[2], o1[3]); *(u32x4*)((bf16_t*)out + off + bj * HALF) = w; }
;                     s += ((o0[0] * o0[0] + o0[1] * o0[1]) + (o0[2] * o0[2] + o0[3] * o0[3])) + ((o1[0] * o1[0] + o1[1] * o1[1]) + (o1[2] * o1[2] + o1[3] * o1[3]));
;                 }
;                 if (ssq) { s += __shfl_xor(s, 16); s += __shfl_xor(s, 32); if (fq == 0) ssq_add(ssq, row, s); }
;             }
.LBB0_2179:
	v_lshl_add_u32 v150, s36, 8, v1
	v_lshl_or_b32 v148, s53, 8, v153
	v_ashrrev_i32_e32 v151, 31, v150
	v_ashrrev_i32_e32 v149, 31, v148
	v_lshlrev_b64 v[146:147], 10, v[150:151]
	v_readlane_b32 s30, v244, 63
	v_lshl_add_u64 v[146:147], v[146:147], 0, v[148:149]
	v_readlane_b32 s31, v243, 0
	v_readlane_b32 s64, v244, 3
	v_readlane_b32 s68, v244, 7
	v_lshl_add_u64 v[162:163], v[146:147], 1, s[30:31]
	global_load_dwordx4 v[158:161], v[162:163], off
	v_readlane_b32 s69, v244, 8
	v_readlane_b32 s70, v244, 9
	v_readlane_b32 s71, v244, 10
	s_mov_b64 s[40:41], s[68:69]
	v_lshl_add_u64 v[164:165], v[146:147], 2, s[40:41]
	s_andn2_b64 vcc, exec, s[0:1]
	s_mov_b64 s[0:1], -1
	v_readlane_b32 s65, v244, 4
	v_readlane_b32 s66, v244, 5
	v_readlane_b32 s67, v244, 6
	s_mov_b64 s[42:43], s[70:71]
	s_waitcnt vmcnt(0)
	v_lshlrev_b32_e32 v166, 16, v158
	v_and_b32_e32 v167, 0xffff0000, v158
	v_lshlrev_b32_e32 v158, 16, v159
	v_and_b32_e32 v159, 0xffff0000, v159
	v_lshlrev_b32_e32 v168, 16, v160
	v_and_b32_e32 v169, 0xffff0000, v160
	v_lshlrev_b32_e32 v160, 16, v161
	v_and_b32_e32 v161, 0xffff0000, v161
	v_pk_fma_f32 v[128:129], v[128:129], 0.5, v[158:159] op_sel_hi:[1,0,1]
	v_pk_fma_f32 v[126:127], v[126:127], 0.5, v[166:167] op_sel_hi:[1,0,1]
	v_pk_fma_f32 v[124:125], v[124:125], 0.5, v[160:161] op_sel_hi:[1,0,1]
	v_pk_fma_f32 v[122:123], v[122:123], 0.5, v[168:169] op_sel_hi:[1,0,1]
	global_store_dwordx4 v[164:165], v[126:129], off nt
	global_store_dwordx4 v[164:165], v[122:125], off offset:16 nt
	global_load_dwordx4 v[122:125], v[162:163], off offset:256
	v_or_b32_e32 v126, 16, v150
	v_ashrrev_i32_e32 v127, 31, v126
	v_lshlrev_b64 v[126:127], 10, v[126:127]
	v_lshl_add_u64 v[126:127], v[126:127], 0, v[148:149]
	v_lshl_add_u64 v[128:129], v[126:127], 1, s[30:31]
	s_waitcnt vmcnt(0)
	v_lshlrev_b32_e32 v158, 16, v122
	v_and_b32_e32 v159, 0xffff0000, v122
	v_lshlrev_b32_e32 v122, 16, v123
	v_and_b32_e32 v123, 0xffff0000, v123
	v_lshlrev_b32_e32 v160, 16, v124
	v_and_b32_e32 v161, 0xffff0000, v124
	v_lshlrev_b32_e32 v124, 16, v125
	v_and_b32_e32 v125, 0xffff0000, v125
	v_pk_fma_f32 v[120:121], v[120:121], 0.5, v[122:123] op_sel_hi:[1,0,1]
	v_pk_fma_f32 v[118:119], v[118:119], 0.5, v[158:159] op_sel_hi:[1,0,1]
	v_pk_fma_f32 v[116:117], v[116:117], 0.5, v[124:125] op_sel_hi:[1,0,1]
	v_pk_fma_f32 v[114:115], v[114:115], 0.5, v[160:161] op_sel_hi:[1,0,1]
	global_store_dwordx4 v[164:165], v[118:121], off offset:512 nt
	global_store_dwordx4 v[164:165], v[114:117], off offset:528 nt
	global_load_dwordx4 v[114:117], v[128:129], off
	v_lshl_add_u64 v[118:119], v[126:127], 2, s[40:41]
	s_waitcnt vmcnt(0)
	v_lshlrev_b32_e32 v120, 16, v114
	v_and_b32_e32 v121, 0xffff0000, v114
	v_lshlrev_b32_e32 v114, 16, v115
	v_and_b32_e32 v115, 0xffff0000, v115
	v_lshlrev_b32_e32 v122, 16, v116
	v_and_b32_e32 v123, 0xffff0000, v116
	v_lshlrev_b32_e32 v116, 16, v117
	v_and_b32_e32 v117, 0xffff0000, v117
	v_pk_fma_f32 v[112:113], v[112:113], 0.5, v[114:115] op_sel_hi:[1,0,1]
	v_pk_fma_f32 v[110:111], v[110:111], 0.5, v[120:121] op_sel_hi:[1,0,1]
	v_pk_fma_f32 v[108:109], v[108:109], 0.5, v[116:117] op_sel_hi:[1,0,1]
	v_pk_fma_f32 v[106:107], v[106:107], 0.5, v[122:123] op_sel_hi:[1,0,1]
	global_store_dwordx4 v[118:119], v[110:113], off nt
	global_store_dwordx4 v[118:119], v[106:109], off offset:16 nt
	global_load_dwordx4 v[106:109], v[128:129], off offset:256
	v_or_b32_e32 v110, 32, v150
	v_ashrrev_i32_e32 v111, 31, v110
	v_lshlrev_b64 v[110:111], 10, v[110:111]
	v_lshl_add_u64 v[110:111], v[110:111], 0, v[148:149]
	v_lshl_add_u64 v[112:113], v[110:111], 1, s[30:31]
	s_waitcnt vmcnt(0)
	v_lshlrev_b32_e32 v114, 16, v106
	v_and_b32_e32 v115, 0xffff0000, v106
	v_lshlrev_b32_e32 v106, 16, v107
	v_and_b32_e32 v107, 0xffff0000, v107
	v_lshlrev_b32_e32 v116, 16, v108
	v_and_b32_e32 v117, 0xffff0000, v108
	v_lshlrev_b32_e32 v108, 16, v109
	v_and_b32_e32 v109, 0xffff0000, v109
	v_pk_fma_f32 v[104:105], v[104:105], 0.5, v[106:107] op_sel_hi:[1,0,1]
	v_pk_fma_f32 v[102:103], v[102:103], 0.5, v[114:115] op_sel_hi:[1,0,1]
	v_pk_fma_f32 v[100:101], v[100:101], 0.5, v[108:109] op_sel_hi:[1,0,1]
	v_pk_fma_f32 v[98:99], v[98:99], 0.5, v[116:117] op_sel_hi:[1,0,1]
	global_store_dwordx4 v[118:119], v[102:105], off offset:512 nt
	global_store_dwordx4 v[118:119], v[98:101], off offset:528 nt
	global_load_dwordx4 v[98:101], v[112:113], off
	v_lshl_add_u64 v[102:103], v[110:111], 2, s[40:41]
	s_waitcnt vmcnt(0)
	v_lshlrev_b32_e32 v104, 16, v98
	v_and_b32_e32 v105, 0xffff0000, v98
	v_lshlrev_b32_e32 v98, 16, v99
	v_and_b32_e32 v99, 0xffff0000, v99
	v_lshlrev_b32_e32 v106, 16, v100
	v_and_b32_e32 v107, 0xffff0000, v100
	v_lshlrev_b32_e32 v100, 16, v101
	v_and_b32_e32 v101, 0xffff0000, v101
	v_pk_fma_f32 v[96:97], v[96:97], 0.5, v[98:99] op_sel_hi:[1,0,1]
	v_pk_fma_f32 v[94:95], v[94:95], 0.5, v[104:105] op_sel_hi:[1,0,1]
	v_pk_fma_f32 v[92:93], v[92:93], 0.5, v[100:101] op_sel_hi:[1,0,1]
	v_pk_fma_f32 v[90:91], v[90:91], 0.5, v[106:107] op_sel_hi:[1,0,1]
	global_store_dwordx4 v[102:103], v[94:97], off nt
	global_store_dwordx4 v[102:103], v[90:93], off offset:16 nt
	global_load_dwordx4 v[90:93], v[112:113], off offset:256
	v_or_b32_e32 v94, 48, v150
	v_ashrrev_i32_e32 v95, 31, v94
	v_lshlrev_b64 v[94:95], 10, v[94:95]
	v_lshl_add_u64 v[94:95], v[94:95], 0, v[148:149]
	v_lshl_add_u64 v[96:97], v[94:95], 1, s[30:31]
	s_waitcnt vmcnt(0)
; DI unsigned pk2(float lo, float hi) { f32x2 v = {lo, hi}; return __builtin_bit_cast(unsigned, __builtin_convertvector(v, bf16v2)); }
;     __device__ __forceinline__ void operator()(const f32x4 (&acc)[2][2][4][2], const Unit& u, int wr, int wc, int fr, int fq, const Pre&) const {
;     ...
;                 const int row = row0 + ai * HALF + m * 16; const size_t off = (size_t)row * DM + col0; float s = 0.f;
; #pragma unroll
;                 for (int bj = 0; bj < 2; ++bj) {
;                     f32x4 b0, b1;
;                     if (BASE_F32) { const float* bp = (const float*)base + off + bj * HALF; b0 = *(const f32x4*)bp; b1 = *(const f32x4*)(bp + 4); }
;                     else { const u32x4 w = *(const u32x4*)((const bf16_t*)base + off + bj * HALF); b0 = (f32x4){bflo(w.x), bfhi(w.x), bflo(w.y), bfhi(w.y)}; b1 = (f32x4){bflo(w.z), bfhi(w.z), bflo(w.w), bfhi(w.w)}; }
;                     const f32x4 o0 = b0 + acc[ai][bj][m][0] * alpha, o1 = b1 + acc[ai][bj][m][1] * alpha;
;                     if (OUT_F32) { float* op = (float*)out + off + bj * HALF; *(f32x4*)op = o0; *(f32x4*)(op + 4) = o1; }
;                     else { u32x4 w; w.x = pk2(o0[0], o0[1]); w.y = pk2(o0[2], o0[3]); w.z = pk2(o1[0], o1[1]); w.w = pk2(o1[2], o1[3]); *(u32x4*)((bf16_t*)out + off + bj * HALF) = w; }
;                     s += ((o0[0] * o0[0] + o0[1] * o0[1]) + (o0[2] * o0[2] + o0[3] * o0[3])) + ((o1[0] * o1[0] + o1[1] * o1[1]) + (o1[2] * o1[2] + o1[3] * o1[3]));
;                 }
	v_lshlrev_b32_e32 v98, 16, v90
	v_and_b32_e32 v99, 0xffff0000, v90
	v_lshlrev_b32_e32 v90, 16, v91
	v_and_b32_e32 v91, 0xffff0000, v91
	v_lshlrev_b32_e32 v100, 16, v92
	v_and_b32_e32 v101, 0xffff0000, v92
	v_lshlrev_b32_e32 v92, 16, v93
	v_and_b32_e32 v93, 0xffff0000, v93
	v_pk_fma_f32 v[88:89], v[88:89], 0.5, v[90:91] op_sel_hi:[1,0,1]
	v_pk_fma_f32 v[86:87], v[86:87], 0.5, v[98:99] op_sel_hi:[1,0,1]
	v_pk_fma_f32 v[84:85], v[84:85], 0.5, v[92:93] op_sel_hi:[1,0,1]
	v_pk_fma_f32 v[82:83], v[82:83], 0.5, v[100:101] op_sel_hi:[1,0,1]
	global_store_dwordx4 v[102:103], v[86:89], off offset:512 nt
	global_store_dwordx4 v[102:103], v[82:85], off offset:528 nt
	global_load_dwordx4 v[82:85], v[96:97], off
	v_lshl_add_u64 v[86:87], v[94:95], 2, s[40:41]
	s_waitcnt vmcnt(0)
	v_lshlrev_b32_e32 v88, 16, v82
	v_and_b32_e32 v89, 0xffff0000, v82
	v_lshlrev_b32_e32 v82, 16, v83
	v_and_b32_e32 v83, 0xffff0000, v83
	v_lshlrev_b32_e32 v90, 16, v84
	v_and_b32_e32 v91, 0xffff0000, v84
	v_lshlrev_b32_e32 v84, 16, v85
	v_and_b32_e32 v85, 0xffff0000, v85
	v_pk_fma_f32 v[80:81], v[80:81], 0.5, v[82:83] op_sel_hi:[1,0,1]
	v_pk_fma_f32 v[78:79], v[78:79], 0.5, v[88:89] op_sel_hi:[1,0,1]
	v_pk_fma_f32 v[76:77], v[76:77], 0.5, v[84:85] op_sel_hi:[1,0,1]
	v_pk_fma_f32 v[74:75], v[74:75], 0.5, v[90:91] op_sel_hi:[1,0,1]
	global_store_dwordx4 v[86:87], v[78:81], off nt
	global_store_dwordx4 v[86:87], v[74:77], off offset:16 nt
	global_load_dwordx4 v[74:77], v[96:97], off offset:256
	v_lshl_add_u64 v[78:79], v[146:147], 0, s[14:15]
	v_lshl_add_u64 v[80:81], v[78:79], 1, s[30:31]
	s_waitcnt vmcnt(0)
	v_lshlrev_b32_e32 v82, 16, v74
	v_and_b32_e32 v83, 0xffff0000, v74
	v_lshlrev_b32_e32 v74, 16, v75
	v_and_b32_e32 v75, 0xffff0000, v75
	v_lshlrev_b32_e32 v84, 16, v76
	v_and_b32_e32 v85, 0xffff0000, v76
	v_lshlrev_b32_e32 v76, 16, v77
	v_and_b32_e32 v77, 0xffff0000, v77
	v_pk_fma_f32 v[72:73], v[72:73], 0.5, v[74:75] op_sel_hi:[1,0,1]
	v_pk_fma_f32 v[70:71], v[70:71], 0.5, v[82:83] op_sel_hi:[1,0,1]
	v_pk_fma_f32 v[68:69], v[68:69], 0.5, v[76:77] op_sel_hi:[1,0,1]
	v_pk_fma_f32 v[66:67], v[66:67], 0.5, v[84:85] op_sel_hi:[1,0,1]
	global_store_dwordx4 v[86:87], v[70:73], off offset:512 nt
	global_store_dwordx4 v[86:87], v[66:69], off offset:528 nt
	global_load_dwordx4 v[66:69], v[80:81], off
	v_lshl_add_u64 v[70:71], v[78:79], 2, s[40:41]
	s_waitcnt vmcnt(0)
	v_lshlrev_b32_e32 v72, 16, v66
	v_and_b32_e32 v73, 0xffff0000, v66
	v_lshlrev_b32_e32 v66, 16, v67
	v_and_b32_e32 v67, 0xffff0000, v67
	v_lshlrev_b32_e32 v74, 16, v68
	v_and_b32_e32 v75, 0xffff0000, v68
	v_lshlrev_b32_e32 v68, 16, v69
	v_and_b32_e32 v69, 0xffff0000, v69
	v_pk_fma_f32 v[64:65], v[64:65], 0.5, v[66:67] op_sel_hi:[1,0,1]
	v_pk_fma_f32 v[62:63], v[62:63], 0.5, v[72:73] op_sel_hi:[1,0,1]
	v_pk_fma_f32 v[60:61], v[60:61], 0.5, v[68:69] op_sel_hi:[1,0,1]
	v_pk_fma_f32 v[58:59], v[58:59], 0.5, v[74:75] op_sel_hi:[1,0,1]
	global_store_dwordx4 v[70:71], v[62:65], off nt
	global_store_dwordx4 v[70:71], v[58:61], off offset:16 nt
	global_load_dwordx4 v[58:61], v[80:81], off offset:256
	v_lshl_add_u64 v[62:63], v[146:147], 0, s[16:17]
	v_lshl_add_u64 v[64:65], v[62:63], 1, s[30:31]
	s_waitcnt vmcnt(0)
	v_lshlrev_b32_e32 v66, 16, v58
	v_and_b32_e32 v67, 0xffff0000, v58
	v_lshlrev_b32_e32 v58, 16, v59
	v_and_b32_e32 v59, 0xffff0000, v59
	v_lshlrev_b32_e32 v68, 16, v60
	v_and_b32_e32 v69, 0xffff0000, v60
	v_lshlrev_b32_e32 v60, 16, v61
	v_and_b32_e32 v61, 0xffff0000, v61
	v_pk_fma_f32 v[56:57], v[56:57], 0.5, v[58:59] op_sel_hi:[1,0,1]
	v_pk_fma_f32 v[54:55], v[54:55], 0.5, v[66:67] op_sel_hi:[1,0,1]
	v_pk_fma_f32 v[52:53], v[52:53], 0.5, v[60:61] op_sel_hi:[1,0,1]
	v_pk_fma_f32 v[50:51], v[50:51], 0.5, v[68:69] op_sel_hi:[1,0,1]
	global_store_dwordx4 v[70:71], v[54:57], off offset:512 nt
	global_store_dwordx4 v[70:71], v[50:53], off offset:528 nt
	global_load_dwordx4 v[50:53], v[64:65], off
	v_lshl_add_u64 v[54:55], v[62:63], 2, s[40:41]
	s_waitcnt vmcnt(0)
; DI unsigned pk2(float lo, float hi) { f32x2 v = {lo, hi}; return __builtin_bit_cast(unsigned, __builtin_convertvector(v, bf16v2)); }
;     __device__ __forceinline__ void operator()(const f32x4 (&acc)[2][2][4][2], const Unit& u, int wr, int wc, int fr, int fq, const Pre&) const {
;     ...
;                 const int row = row0 + ai * HALF + m * 16; const size_t off = (size_t)row * DM + col0; float s = 0.f;
; #pragma unroll
;                 for (int bj = 0; bj < 2; ++bj) {
;                     f32x4 b0, b1;
;                     if (BASE_F32) { const float* bp = (const float*)base + off + bj * HALF; b0 = *(const f32x4*)bp; b1 = *(const f32x4*)(bp + 4); }
;                     else { const u32x4 w = *(const u32x4*)((const bf16_t*)base + off + bj * HALF); b0 = (f32x4){bflo(w.x), bfhi(w.x), bflo(w.y), bfhi(w.y)}; b1 = (f32x4){bflo(w.z), bfhi(w.z), bflo(w.w), bfhi(w.w)}; }
;                     const f32x4 o0 = b0 + acc[ai][bj][m][0] * alpha, o1 = b1 + acc[ai][bj][m][1] * alpha;
;                     if (OUT_F32) { float* op = (float*)out + off + bj * HALF; *(f32x4*)op = o0; *(f32x4*)(op + 4) = o1; }
;                     else { u32x4 w; w.x = pk2(o0[0], o0[1]); w.y = pk2(o0[2], o0[3]); w.z = pk2(o1[0], o1[1]); w.w = pk2(o1[2], o1[3]); *(u32x4*)((bf16_t*)out + off + bj * HALF) = w; }
;                     s += ((o0[0] * o0[0] + o0[1] * o0[1]) + (o0[2] * o0[2] + o0[3] * o0[3])) + ((o1[0] * o1[0] + o1[1] * o1[1]) + (o1[2] * o1[2] + o1[3] * o1[3]));
;                 }
	v_lshlrev_b32_e32 v56, 16, v50
	v_and_b32_e32 v57, 0xffff0000, v50
	v_lshlrev_b32_e32 v50, 16, v51
	v_and_b32_e32 v51, 0xffff0000, v51
	v_lshlrev_b32_e32 v58, 16, v52
	v_and_b32_e32 v59, 0xffff0000, v52
	v_lshlrev_b32_e32 v52, 16, v53
	v_and_b32_e32 v53, 0xffff0000, v53
	v_pk_fma_f32 v[48:49], v[48:49], 0.5, v[50:51] op_sel_hi:[1,0,1]
	v_pk_fma_f32 v[46:47], v[46:47], 0.5, v[56:57] op_sel_hi:[1,0,1]
	v_pk_fma_f32 v[44:45], v[44:45], 0.5, v[52:53] op_sel_hi:[1,0,1]
	v_pk_fma_f32 v[42:43], v[42:43], 0.5, v[58:59] op_sel_hi:[1,0,1]
	global_store_dwordx4 v[54:55], v[46:49], off nt
	global_store_dwordx4 v[54:55], v[42:45], off offset:16 nt
	global_load_dwordx4 v[42:45], v[64:65], off offset:256
	v_lshl_add_u64 v[46:47], v[146:147], 0, s[18:19]
	v_lshl_add_u64 v[48:49], v[46:47], 1, s[30:31]
	s_waitcnt vmcnt(0)
	v_lshlrev_b32_e32 v50, 16, v42
	v_and_b32_e32 v51, 0xffff0000, v42
	v_lshlrev_b32_e32 v42, 16, v43
	v_and_b32_e32 v43, 0xffff0000, v43
	v_lshlrev_b32_e32 v52, 16, v44
	v_and_b32_e32 v53, 0xffff0000, v44
	v_lshlrev_b32_e32 v44, 16, v45
	v_and_b32_e32 v45, 0xffff0000, v45
	v_pk_fma_f32 v[40:41], v[40:41], 0.5, v[42:43] op_sel_hi:[1,0,1]
	v_pk_fma_f32 v[38:39], v[38:39], 0.5, v[50:51] op_sel_hi:[1,0,1]
	v_pk_fma_f32 v[36:37], v[36:37], 0.5, v[44:45] op_sel_hi:[1,0,1]
	v_pk_fma_f32 v[34:35], v[34:35], 0.5, v[52:53] op_sel_hi:[1,0,1]
	global_store_dwordx4 v[54:55], v[38:41], off offset:512 nt
	global_store_dwordx4 v[54:55], v[34:37], off offset:528 nt
	global_load_dwordx4 v[34:37], v[48:49], off
	v_lshl_add_u64 v[38:39], v[46:47], 2, s[40:41]
	s_waitcnt vmcnt(0)
	v_lshlrev_b32_e32 v40, 16, v34
	v_and_b32_e32 v41, 0xffff0000, v34
	v_lshlrev_b32_e32 v34, 16, v35
	v_and_b32_e32 v35, 0xffff0000, v35
	v_lshlrev_b32_e32 v42, 16, v36
	v_and_b32_e32 v43, 0xffff0000, v36
	v_lshlrev_b32_e32 v36, 16, v37
	v_and_b32_e32 v37, 0xffff0000, v37
	v_pk_fma_f32 v[32:33], v[32:33], 0.5, v[34:35] op_sel_hi:[1,0,1]
	v_pk_fma_f32 v[30:31], v[30:31], 0.5, v[40:41] op_sel_hi:[1,0,1]
	v_pk_fma_f32 v[28:29], v[28:29], 0.5, v[36:37] op_sel_hi:[1,0,1]
	v_pk_fma_f32 v[26:27], v[26:27], 0.5, v[42:43] op_sel_hi:[1,0,1]
	global_store_dwordx4 v[38:39], v[30:33], off nt
	global_store_dwordx4 v[38:39], v[26:29], off offset:16 nt
	global_load_dwordx4 v[26:29], v[48:49], off offset:256
	v_lshl_add_u64 v[30:31], v[146:147], 0, s[20:21]
	v_lshl_add_u64 v[32:33], v[30:31], 1, s[30:31]
	s_waitcnt vmcnt(0)
	v_lshlrev_b32_e32 v34, 16, v26
	v_and_b32_e32 v35, 0xffff0000, v26
	v_lshlrev_b32_e32 v26, 16, v27
	v_and_b32_e32 v27, 0xffff0000, v27
	v_lshlrev_b32_e32 v36, 16, v28
	v_and_b32_e32 v37, 0xffff0000, v28
	v_lshlrev_b32_e32 v28, 16, v29
	v_and_b32_e32 v29, 0xffff0000, v29
	v_pk_fma_f32 v[24:25], v[24:25], 0.5, v[26:27] op_sel_hi:[1,0,1]
	v_pk_fma_f32 v[22:23], v[22:23], 0.5, v[34:35] op_sel_hi:[1,0,1]
	v_pk_fma_f32 v[20:21], v[20:21], 0.5, v[28:29] op_sel_hi:[1,0,1]
	v_pk_fma_f32 v[18:19], v[18:19], 0.5, v[36:37] op_sel_hi:[1,0,1]
	global_store_dwordx4 v[38:39], v[22:25], off offset:512 nt
	global_store_dwordx4 v[38:39], v[18:21], off offset:528 nt
	global_load_dwordx4 v[18:21], v[32:33], off
	v_lshl_add_u64 v[22:23], v[30:31], 2, s[40:41]
	s_waitcnt vmcnt(0)
	v_lshlrev_b32_e32 v24, 16, v18
	v_and_b32_e32 v25, 0xffff0000, v18
	v_lshlrev_b32_e32 v18, 16, v19
	v_and_b32_e32 v19, 0xffff0000, v19
	v_lshlrev_b32_e32 v26, 16, v20
	v_and_b32_e32 v27, 0xffff0000, v20
	v_lshlrev_b32_e32 v20, 16, v21
	v_and_b32_e32 v21, 0xffff0000, v21
	v_pk_fma_f32 v[16:17], v[16:17], 0.5, v[18:19] op_sel_hi:[1,0,1]
	v_pk_fma_f32 v[14:15], v[14:15], 0.5, v[24:25] op_sel_hi:[1,0,1]
	v_pk_fma_f32 v[12:13], v[12:13], 0.5, v[20:21] op_sel_hi:[1,0,1]
	v_pk_fma_f32 v[10:11], v[10:11], 0.5, v[26:27] op_sel_hi:[1,0,1]
	global_store_dwordx4 v[22:23], v[14:17], off nt
	global_store_dwordx4 v[22:23], v[10:13], off offset:16 nt
	global_load_dwordx4 v[10:13], v[32:33], off offset:256
	s_waitcnt vmcnt(0)
	v_lshlrev_b32_e32 v14, 16, v10
	v_and_b32_e32 v15, 0xffff0000, v10
	v_lshlrev_b32_e32 v10, 16, v11
	v_and_b32_e32 v11, 0xffff0000, v11
	v_lshlrev_b32_e32 v16, 16, v12
	v_and_b32_e32 v17, 0xffff0000, v12
	v_lshlrev_b32_e32 v12, 16, v13
	v_and_b32_e32 v13, 0xffff0000, v13
	v_pk_fma_f32 v[8:9], v[8:9], 0.5, v[10:11] op_sel_hi:[1,0,1]
	v_pk_fma_f32 v[6:7], v[6:7], 0.5, v[14:15] op_sel_hi:[1,0,1]
	v_pk_fma_f32 v[4:5], v[4:5], 0.5, v[12:13] op_sel_hi:[1,0,1]
	v_pk_fma_f32 v[2:3], v[2:3], 0.5, v[16:17] op_sel_hi:[1,0,1]
	global_store_dwordx4 v[22:23], v[6:9], off offset:512 nt
	global_store_dwordx4 v[22:23], v[2:5], off offset:528 nt
	s_cbranch_vccnz .LBB0_2168
	s_andn2_b64 vcc, exec, s[8:9]
	s_cbranch_vccnz .LBB0_2167
	s_barrier
	s_branch .LBB0_2167

; __device__ __forceinline__ unsigned xb_ld(unsigned* p)              { return __hip_atomic_load(p, __ATOMIC_RELAXED, __HIP_MEMORY_SCOPE_AGENT); }
; __device__ __forceinline__ unsigned xb_add(unsigned* p, unsigned v) { return __hip_atomic_fetch_add(p, v, __ATOMIC_RELAXED, __HIP_MEMORY_SCOPE_AGENT); }
; #define XB_SPIN(cond, bar) do { unsigned _sp = 0; while (cond) { __builtin_amdgcn_s_sleep(1); \
;     if ((++_sp & 255u) == 0u) { if (xb_ld(&(bar)[XB_TMO])) break; if (_sp > XB_SPIN_CAP) { atomicAdd(&(bar)[XB_TMO], 1u); break; } } } } while (0)
; __device__ __forceinline__ void xcd_barrier(const XcdBarrier& b) {
;     ...
;         const unsigned old = xb_add(&bar[XB_XSUB(b.x)], 1u);
;         const unsigned gen = old / nloc;
;         if (old + 1u == (gen + 1u) * nloc) {
;             __builtin_amdgcn_fence(__ATOMIC_RELEASE, "agent");
;             asm volatile("s_waitcnt vmcnt(0)" ::: "memory");
;             const unsigned og = xb_add(&bar[XB_TOP], 1u);
;             const unsigned tg = og / nx;
;             if (og + 1u == (tg + 1u) * nx) xb_add(&bar[XB_TOPGEN], 1u);
;             else XB_SPIN(xb_ld(&bar[XB_TOPGEN]) == tg, bar);
;             __builtin_amdgcn_fence(__ATOMIC_ACQUIRE, "agent");
;             xb_add(&bar[XB_XGEN(b.x)], 1u);
;             asm volatile("s_waitcnt vmcnt(0)" ::: "memory");
;         } else {
;             XB_SPIN(xb_ld(&bar[XB_XGEN(b.x)]) == gen, bar);
.LBB0_2216:
	s_lshl_b32 s2, s97, 8
	s_add_u32 s2, s94, s2
	s_addc_u32 s3, s95, 0
	v_mov_b32_e32 v1, 0x1000
	v_mov_b32_e32 v3, 1
	global_atomic_add v3, v1, v3, s[2:3] offset:1024 sc0
	v_cvt_f32_u32_e32 v1, v2
	v_sub_u32_e32 v4, 0, v2
	v_rcp_iflag_f32_e32 v1, v1
	s_nop 0
	v_mul_f32_e32 v1, 0x4f7ffffe, v1
	v_cvt_u32_f32_e32 v1, v1
	v_mul_lo_u32 v4, v4, v1
	v_mul_hi_u32 v4, v1, v4
	v_add_u32_e32 v1, v1, v4
	s_waitcnt vmcnt(0)
	v_mul_hi_u32 v1, v3, v1
	v_mul_lo_u32 v4, v1, v2
	v_sub_u32_e32 v4, v3, v4
	v_add_u32_e32 v5, 1, v1
	v_cmp_ge_u32_e32 vcc, v4, v2
	v_add_u32_e32 v3, 1, v3
	s_nop 0
	v_cndmask_b32_e32 v1, v1, v5, vcc
	v_sub_u32_e32 v5, v4, v2
	v_cndmask_b32_e32 v4, v4, v5, vcc
	v_add_u32_e32 v5, 1, v1
	v_cmp_ge_u32_e32 vcc, v4, v2
	s_nop 1
	v_cndmask_b32_e32 v1, v1, v5, vcc
	v_mul_lo_u32 v4, v2, v1
	v_add_u32_e32 v2, v4, v2
	v_cmp_ne_u32_e32 vcc, v3, v2
	s_and_saveexec_b64 s[4:5], vcc
	s_xor_b64 s[4:5], exec, s[4:5]
	s_cbranch_execz .LBB0_2230
	s_waitcnt lgkmcnt(0)
	buffer_inv sc1
	v_mov_b32_e32 v0, 0x2000
	global_load_dword v0, v0, s[2:3] offset:1024 sc1
	s_add_u32 s10, s2, 0x2400
	s_addc_u32 s11, s3, 0
	s_waitcnt vmcnt(0)
	v_cmp_eq_u32_e32 vcc, v0, v1
	s_and_saveexec_b64 s[6:7], vcc
	s_cbranch_execz .LBB0_2229
	v_readlane_b32 s12, v244, 3
	v_readlane_b32 s14, v244, 5
	v_readlane_b32 s15, v244, 6
	v_readlane_b32 s18, v244, 9
	v_readlane_b32 s19, v244, 10
	s_mov_b64 s[14:15], s[18:19]
	v_readlane_b32 s13, v244, 4
	s_add_u32 s8, s14, 0x4200
	s_addc_u32 s9, s15, 0
	s_mov_b32 s22, 1
	s_mov_b64 s[12:13], 0
	v_mov_b32_e32 v0, 0
	v_readlane_b32 s16, v244, 7
	v_readlane_b32 s17, v244, 8
	s_branch .LBB0_2220

; __device__ __forceinline__ unsigned xb_ld(unsigned* p)              { return __hip_atomic_load(p, __ATOMIC_RELAXED, __HIP_MEMORY_SCOPE_AGENT); }
; #define XB_SPIN(cond, bar) do { unsigned _sp = 0; while (cond) { __builtin_amdgcn_s_sleep(1); \
;     if ((++_sp & 255u) == 0u) { if (xb_ld(&(bar)[XB_TMO])) break; if (_sp > XB_SPIN_CAP) { atomicAdd(&(bar)[XB_TMO], 1u); break; } } } } while (0)
; __device__ __forceinline__ void xcd_barrier(const XcdBarrier& b) {
;     ...
;             XB_SPIN(xb_ld(&bar[XB_XGEN(b.x)]) == gen, bar);
;             __builtin_amdgcn_fence(__ATOMIC_ACQUIRE, "agent");
;             asm volatile("s_waitcnt vmcnt(0)" ::: "memory");
.LBB0_2229:
	s_or_b64 exec, exec, s[6:7]
	s_waitcnt vmcnt(0)
	s_waitcnt vmcnt(0)
